# attention: K tile as two bank-conflict-free planes (pitch 160), QK^T latent groups regenerated with all LDS reads issued up front
# speedup vs baseline: 1.0112x; 1.0075x over previous
; #define LAS __attribute__((address_space(3)))
; template <bool CTXQ>
; __device__ __forceinline__ void attn_super(const bf16_t* QO, bf16_t* OO, const bf16_t* Kb, const bf16_t* VT, const float* rpb, LAS unsigned char* lds, int tid_, int lane_, int wave, int st) {
;     ...
;     else { const int rp = st & 31; h = (st >> 5) & 15; b = st >> 9; r = 2 * rp + (wave >> 2); q0 = (wave & 3) * 16; ks = min(max(q0 - 8, 0), 32); rs = min(max(r - 4, 0), 56);
;         kbase = min(min(max(2 * rp - 4, 0), 56), 55); krl0 = rs - kbase; qrow = (size_t)b * SEQ + r * 64 + q0 + q; }
;     u32x4 stg[13];
; #pragma unroll
;     for (int i = I0; i < 13; ++i) { const int c = tid + 512 * i, t = c >> 3, cc = c & 7;
;         const size_t urow = t < 576 ? (size_t)b * SEQ + kbase * 64 + t : (size_t)ML + b * CTXL + (t - 576);
;         stg[i] = *(const u32x4*)(Kb + urow * DM + h * 64 + cc * 8); }
;     const bf16x8 qf0 = *(const bf16x8*)(QO + qrow * DM + h * 64 + 8 * g), qf1 = *(const bf16x8*)(QO + qrow * DM + h * 64 + 32 + 8 * g);
;     LAS float* rpl = (LAS float*)(lds + 832 * AT_PITCH);
;     if (!CTXQ) { if (tid < 465) rpl[tid] = rpb[h * 465 + tid] * 1.4426950408889634f; }
; #pragma unroll
;     for (int i = I0; i < 13; ++i) { const int c = tid + 512 * i, t = c >> 3, cc = c & 7; *(LAS u32x4*)(lds + t * AT_PITCH + cc * 16) = stg[i]; }
;     __syncthreads();
;     const int qcol = q0 + q, wstart = min(max(qcol - 8, 0), 48);
;     const int koff = 8 * (q >> 2) + (q & 3);
;     const LAS float* bptr[2][4]; float madd[2][4];
; #pragma unroll
;     for (int T = 0; T < 2; ++T)
; #pragma unroll
;         for (int j = 0; j < 4; ++j) { const int kcol = ks + 8 * g + 4 * T + j; const bool ok = (kcol >= wstart) && (kcol < wstart + 16);
;             const int dcol = min(max(kcol - qcol + 15, 0), 30);
;             bptr[T][j] = rpl + (rs - r + 7) * 31 + dcol; madd[T][j] = ok ? 0.0f : -1e30f; }
.LBB0_164:
	s_and_b64 vcc, exec, s[2:3]
	s_cbranch_vccz .LBB0_238
	s_ashr_i32 s19, s16, 3
	s_lshl_b32 s3, s19, 1
	s_and_b32 s3, s3, 62
	s_ashr_i32 s6, s18, 8
	s_add_i32 s6, s3, s6
	s_lshl_b32 s17, s17, 4
	s_and_b32 s18, s17, 48
	s_lshl_b32 s7, s6, 6
	v_sub_u32_e64 v0, s3, 4 clamp
	s_ashr_i32 s23, s7, 31
	s_or_b32 s24, s7, s18
	s_max_i32 s7, s6, 4
	v_readfirstlane_b32 s3, v0
	s_add_i32 s7, s7, -4
	s_min_u32 s3, s3, 55
	s_min_u32 s7, s7, 56
	s_lshl_b32 s8, s3, 6
	s_sub_i32 s3, s7, s3
	v_sub_u32_e64 v0, s18, 8 clamp
	s_sub_i32 s6, s7, s6
	s_and_b32 s22, s16, 7
	v_readfirstlane_b32 s10, v0
	s_mulk_i32 s6, 0x7c
	s_lshl_b32 s29, s3, 6
	s_lshl_b32 s2, s22, 5
	s_mov_b32 s73, s57
	s_mov_b32 s9, s57
	s_min_u32 s25, s10, 32
	s_add_i32 s28, s6, 0
	s_add_i32 s31, s29, 64
	s_add_i32 s35, s29, 0x80
	s_add_i32 s37, s29, 0xc0
	s_add_i32 s39, s29, 0x100
	s_add_i32 s51, s29, 0x140
	s_add_i32 s55, s29, 0x180
	s_add_i32 s57, s29, 0x1c0
	s_add_i32 s28, s28, 0x20900
	s_or_b32 s30, s29, s25
	s_or_b32 s34, s31, s25
	s_or_b32 s36, s35, s25
	s_or_b32 s38, s37, s25
	s_or_b32 s50, s39, s25
	s_or_b32 s54, s51, s25
	s_or_b32 s56, s55, s25
	s_or_b32 s59, s57, s25
	s_or_b32 s63, s2, s19
	s_mov_b32 s64, 0
	s_branch .LBB0_167
.LBB0_166:
	s_or_b64 exec, exec, s[2:3]
	v_lshlrev_b32_e32 v65, 4, v104
	v_and_b32_e32 v65, 0x70, v65
	v_add_u32_e32 v102, 0, v65
	v_lshlrev_b64 v[100:101], 10, v[88:89]
	v_lshrrev_b32_e32 v203, 6, v220
	v_bfe_u32 v204, v220, 3, 2
	v_lshl_add_u32 v203, v203, 2, v204
	v_mul_u32_u24_e32 v203, 0xa0, v203
	v_bfe_u32 v204, v220, 5, 1
	v_mul_u32_u24_e32 v204, 0x10400, v204
	v_add3_u32 v203, v203, v204, v102
	v_add_u32_e32 v203, 0x70, v203
	s_waitcnt vmcnt(14)
	ds_write_b128 v203, v[8:11]
	s_waitcnt vmcnt(13)
	ds_write_b128 v203, v[12:15] offset:5120
	s_waitcnt vmcnt(12)
	ds_write_b128 v203, v[16:19] offset:10240
	s_waitcnt vmcnt(11)
	ds_write_b128 v203, v[20:23] offset:15360
	s_waitcnt vmcnt(10)
	ds_write_b128 v203, v[24:27] offset:20480
	s_waitcnt vmcnt(9)
	ds_write_b128 v203, v[28:31] offset:25600
	s_waitcnt vmcnt(8)
	ds_write_b128 v203, v[32:35] offset:30720
	s_waitcnt vmcnt(7)
	ds_write_b128 v203, v[36:39] offset:35840
	s_waitcnt vmcnt(6)
	ds_write_b128 v203, v[40:43] offset:40960
	v_lshlrev_b32_e32 v98, 3, v63
	s_waitcnt vmcnt(5)
	ds_write_b128 v203, v[44:47] offset:46080
	s_waitcnt vmcnt(4)
	ds_write_b128 v203, v[50:53] offset:51200
	v_or_b32_e32 v16, s18, v99
	v_add_u32_e32 v105, s25, v98
	s_waitcnt vmcnt(3)
	ds_write_b128 v203, v[54:57] offset:56320
	v_sub_u32_e32 v10, v105, v16
	s_waitcnt vmcnt(2)
	ds_write_b128 v203, v[58:61] offset:61440
	v_sub_u32_e64 v8, v16, 8 clamp
	v_max_i32_e32 v10, -15, v10
	v_min_u32_e32 v12, 48, v8
	v_add_u32_e32 v10, 15, v10
	v_add_u32_e32 v13, 16, v12
	v_min_u32_e32 v10, 30, v10
	v_cmp_ge_u32_e32 vcc, v105, v12
	v_cmp_lt_u32_e64 s[40:41], v105, v13
	v_lshl_add_u32 v41, v10, 2, s28
	v_or_b32_e32 v10, 1, v105
	s_and_b64 s[2:3], vcc, s[40:41]
	v_cmp_ge_u32_e32 vcc, v10, v12
	v_cmp_lt_u32_e64 s[40:41], v10, v13
	v_sub_u32_e32 v10, v10, v16
	v_max_i32_e32 v10, -15, v10
	v_add_u32_e32 v10, 15, v10
	v_min_u32_e32 v10, 30, v10
	v_lshl_add_u32 v43, v10, 2, s28
	v_or_b32_e32 v10, 2, v105
	v_cndmask_b32_e64 v42, v233, 0, s[2:3]
	s_and_b64 s[2:3], vcc, s[40:41]
	v_cmp_ge_u32_e32 vcc, v10, v12
	v_cmp_lt_u32_e64 s[40:41], v10, v13
	v_sub_u32_e32 v10, v10, v16
	v_max_i32_e32 v10, -15, v10
	v_add_u32_e32 v10, 15, v10
	v_min_u32_e32 v10, 30, v10
	v_lshl_add_u32 v45, v10, 2, s28
	v_or_b32_e32 v10, 3, v105
	v_cndmask_b32_e64 v44, v233, 0, s[2:3]
	s_and_b64 s[2:3], vcc, s[40:41]
	v_cmp_ge_u32_e32 vcc, v10, v12
	v_cmp_lt_u32_e64 s[40:41], v10, v13
	v_sub_u32_e32 v10, v10, v16
	v_max_i32_e32 v10, -15, v10
	v_add_u32_e32 v10, 15, v10
	v_min_u32_e32 v10, 30, v10
	v_lshl_add_u32 v47, v10, 2, s28
	v_or_b32_e32 v10, 4, v105
	v_cndmask_b32_e64 v46, v233, 0, s[2:3]
	s_and_b64 s[2:3], vcc, s[40:41]
	v_cmp_ge_u32_e32 vcc, v10, v12
	v_cmp_lt_u32_e64 s[40:41], v10, v13
	v_sub_u32_e32 v10, v10, v16
	v_max_i32_e32 v10, -15, v10
	v_add_u32_e32 v10, 15, v10
	v_min_u32_e32 v10, 30, v10
	v_lshl_add_u32 v38, v10, 2, s28
	v_or_b32_e32 v10, 5, v105
	v_cndmask_b32_e64 v50, v233, 0, s[2:3]
	s_and_b64 s[2:3], vcc, s[40:41]
	v_cmp_ge_u32_e32 vcc, v10, v12
	v_cmp_lt_u32_e64 s[40:41], v10, v13
	v_sub_u32_e32 v10, v10, v16
	v_max_i32_e32 v10, -15, v10
	v_add_u32_e32 v10, 15, v10
	v_min_u32_e32 v10, 30, v10
	v_lshl_add_u32 v35, v10, 2, s28
	v_or_b32_e32 v10, 6, v105
	v_lshlrev_b32_e32 v8, 1, v99
	v_and_b32_e32 v9, 3, v104
	v_cndmask_b32_e64 v39, v233, 0, s[2:3]
	s_and_b64 s[2:3], vcc, s[40:41]
	v_cmp_ge_u32_e32 vcc, v10, v12
	v_cmp_lt_u32_e64 s[40:41], v10, v13
	v_sub_u32_e32 v10, v10, v16
	v_max_i32_e32 v10, -15, v10
	v_and_or_b32 v32, v8, 24, v9
	v_add_u32_e32 v10, 15, v10
	v_lshl_add_u32 v103, v63, 4, 0
	v_and_b32_e32 v205, 3, v99
	v_mul_u32_u24_e32 v205, 0x50, v205
	v_add_u32_e32 v205, v205, v103
	v_add_u32_e32 v205, 0x70, v205
	v_mov_b32_e32 v206, 0x50
	v_mov_b32_e32 v208, 0xa0
	v_add_u32_e32 v209, 0x70, v103
	v_add_u32_e32 v8, s30, v32
	v_min_u32_e32 v10, 30, v10
	v_mad_u32_u24 v17, v8, v206, v205
	v_add_u32_e32 v207, 0x10400, v17
	s_waitcnt lgkmcnt(0)
	s_barrier
; #define LAS __attribute__((address_space(3)))
; __device__ __forceinline__ f32x4 mfma16(bf16x8 a, bf16x8 b, f32x4 c) { return __builtin_amdgcn_mfma_f32_16x16x32_bf16(a, b, c, 0, 0, 0); }
; template <bool CTXQ>
; __device__ __forceinline__ void attn_super(const bf16_t* QO, bf16_t* OO, const bf16_t* Kb, const bf16_t* VT, const float* rpb, LAS unsigned char* lds, int tid_, int lane_, int wave, int st) {
;     ...
;     for (int grp = G0; grp < 16; ++grp) {
;         const int tb = grp < 8 ? (krl0 + grp) * 64 + ks : 576 + 32 * (grp - 8);
; #pragma unroll
;         for (int T = 0; T < 2; ++T) {
;             const LAS unsigned char* kp = lds + (tb + koff + 4 * T) * AT_PITCH + g * 16;
;             const bf16x8 kf0 = *(const LAS bf16x8*)kp, kf1 = *(const LAS bf16x8*)(kp + 64);
;             f32x4 s = {0.f, 0.f, 0.f, 0.f};
;             s = mfma16(kf0, qf0, s); s = mfma16(kf1, qf1, s);
;             if (grp < 8) {
; #pragma unroll
;                 for (int j = 0; j < 4; ++j) s[j] += bptr[T][j][grp * 31] + madd[T][j];
;             }
;             S[grp][T] = s;
;         }
;         __builtin_amdgcn_sched_barrier(0);
;     }
	v_lshl_add_u32 v34, v10, 2, s28
	ds_read_b128 v[8:11], v17
	v_or_b32_e32 v18, 7, v105
	v_cndmask_b32_e64 v37, v233, 0, s[2:3]
	s_and_b64 s[2:3], vcc, s[40:41]
	v_cmp_ge_u32_e32 vcc, v18, v12
	v_cmp_lt_u32_e64 s[40:41], v18, v13
	ds_read_b128 v[12:15], v17 offset:64
	v_sub_u32_e32 v16, v18, v16
	s_waitcnt vmcnt(1) lgkmcnt(1)
	v_mfma_f32_16x16x32_bf16 v[8:11], v[8:11], v[4:7], 0
	v_max_i32_e32 v16, -15, v16
	v_add_u32_e32 v16, 15, v16
	v_min_u32_e32 v16, 30, v16
	v_lshl_add_u32 v40, v16, 2, s28
	s_waitcnt vmcnt(0) lgkmcnt(0)
	v_mfma_f32_16x16x32_bf16 v[8:11], v[12:15], v[0:3], v[8:11]
	ds_read_b128 v[12:15], v207
	ds_read_b32 v16, v41 offset:868
	ds_read_b32 v18, v43 offset:868
	ds_read_b32 v24, v45 offset:868
	ds_read_b32 v25, v47 offset:868
	ds_read_b32 v26, v38 offset:868
	ds_read_b32 v27, v35 offset:868
	ds_read_b32 v28, v34 offset:868
	ds_read_b32 v29, v40 offset:868
	ds_read_b128 v[20:23], v207 offset:64
	s_waitcnt lgkmcnt(8)
	v_add_f32_e32 v16, v42, v16
	v_mfma_f32_16x16x32_bf16 v[12:15], v[12:15], v[4:7], 0
	v_add_f32_e32 v19, v8, v16
	s_waitcnt lgkmcnt(7)
	v_add_f32_e32 v8, v44, v18
	v_add_f32_e32 v18, v9, v8
	s_waitcnt lgkmcnt(0)
	v_mfma_f32_16x16x32_bf16 v[20:23], v[20:23], v[0:3], v[12:15]
	v_add_f32_e32 v8, v46, v24
	v_add_f32_e32 v17, v10, v8
	v_add_f32_e32 v8, v50, v25
	v_add_f32_e32 v16, v11, v8
	v_add_f32_e32 v8, v39, v26
	v_cndmask_b32_e64 v36, v233, 0, s[2:3]
	s_and_b64 s[2:3], vcc, s[40:41]
	s_nop 0
	v_add_f32_e32 v15, v20, v8
	v_add_f32_e32 v8, v37, v27
	v_cndmask_b32_e64 v33, v233, 0, s[2:3]
	v_add_f32_e32 v13, v21, v8
	v_add_f32_e32 v8, v36, v28
	v_add_f32_e32 v11, v22, v8
	v_add_f32_e32 v8, v33, v29
	v_add_f32_e32 v10, v23, v8
	v_add_u32_e32 v8, s34, v32
	v_mad_u32_u24 v28, v8, v206, v205
	v_add_u32_e32 v207, 0x10400, v28
	ds_read_b128 v[150:153], v28
	ds_read_b128 v[154:157], v28 offset:64
	ds_read_b128 v[158:161], v207
	ds_read_b128 v[162:165], v207 offset:64
	ds_read_b32 v176, v41 offset:992
	ds_read_b32 v177, v43 offset:992
	ds_read_b32 v178, v45 offset:992
	ds_read_b32 v179, v47 offset:992
	ds_read_b32 v180, v38 offset:992
	ds_read_b32 v181, v35 offset:992
	ds_read_b32 v182, v34 offset:992
	ds_read_b32 v183, v40 offset:992
	s_waitcnt lgkmcnt(11)
	v_mfma_f32_16x16x32_bf16 v[166:169], v[150:153], v[4:7], 0
	s_waitcnt lgkmcnt(10)
	v_mfma_f32_16x16x32_bf16 v[166:169], v[154:157], v[0:3], v[166:169]
	s_waitcnt lgkmcnt(9)
	v_mfma_f32_16x16x32_bf16 v[170:173], v[158:161], v[4:7], 0
	s_waitcnt lgkmcnt(8)
	v_mfma_f32_16x16x32_bf16 v[170:173], v[162:165], v[0:3], v[170:173]
	s_waitcnt lgkmcnt(0)
	v_add_f32_e32 v176, v42, v176
	v_add_f32_e32 v177, v44, v177
	v_add_f32_e32 v178, v46, v178
	v_add_f32_e32 v179, v50, v179
	v_add_f32_e32 v180, v39, v180
	v_add_f32_e32 v181, v37, v181
	v_add_f32_e32 v182, v36, v182
	v_add_f32_e32 v183, v33, v183
	v_add_f32_e32 v8, v166, v176
	v_add_f32_e32 v9, v167, v177
	v_add_f32_e32 v12, v168, v178
	v_add_f32_e32 v14, v169, v179
	v_add_f32_e32 v20, v170, v180
	v_add_f32_e32 v21, v171, v181
	v_add_f32_e32 v22, v172, v182
	v_add_f32_e32 v25, v173, v183
	v_add_u32_e32 v23, s36, v32
	v_mad_u32_u24 v51, v23, v206, v205
	v_add_u32_e32 v207, 0x10400, v51
	ds_read_b128 v[150:153], v51
	ds_read_b128 v[154:157], v51 offset:64
	ds_read_b128 v[158:161], v207
	ds_read_b128 v[162:165], v207 offset:64
	ds_read_b32 v176, v41 offset:1116
	ds_read_b32 v177, v43 offset:1116
	ds_read_b32 v178, v45 offset:1116
	ds_read_b32 v179, v47 offset:1116
	ds_read_b32 v180, v38 offset:1116
	ds_read_b32 v181, v35 offset:1116
	ds_read_b32 v182, v34 offset:1116
	ds_read_b32 v183, v40 offset:1116
	s_waitcnt lgkmcnt(11)
	v_mfma_f32_16x16x32_bf16 v[166:169], v[150:153], v[4:7], 0
	s_waitcnt lgkmcnt(10)
	v_mfma_f32_16x16x32_bf16 v[166:169], v[154:157], v[0:3], v[166:169]
	s_waitcnt lgkmcnt(9)
	v_mfma_f32_16x16x32_bf16 v[170:173], v[158:161], v[4:7], 0
	s_waitcnt lgkmcnt(8)
	v_mfma_f32_16x16x32_bf16 v[170:173], v[162:165], v[0:3], v[170:173]
	s_waitcnt lgkmcnt(0)
	v_add_f32_e32 v176, v42, v176
	v_add_f32_e32 v177, v44, v177
	v_add_f32_e32 v178, v46, v178
	v_add_f32_e32 v179, v50, v179
	v_add_f32_e32 v180, v39, v180
	v_add_f32_e32 v181, v37, v181
	v_add_f32_e32 v182, v36, v182
	v_add_f32_e32 v183, v33, v183
	v_add_f32_e32 v23, v166, v176
	v_add_f32_e32 v24, v167, v177
	v_add_f32_e32 v26, v168, v178
	v_add_f32_e32 v27, v169, v179
	v_add_f32_e32 v28, v170, v180
	v_add_f32_e32 v29, v171, v181
	v_add_f32_e32 v30, v172, v182
	v_add_f32_e32 v109, v173, v183
	v_add_u32_e32 v31, s38, v32
	v_mad_u32_u24 v51, v31, v206, v205
	v_add_u32_e32 v207, 0x10400, v51
	ds_read_b128 v[150:153], v51
	ds_read_b128 v[154:157], v51 offset:64
	ds_read_b128 v[158:161], v207
	ds_read_b128 v[162:165], v207 offset:64
	ds_read_b32 v176, v41 offset:1240
	ds_read_b32 v177, v43 offset:1240
	ds_read_b32 v178, v45 offset:1240
	ds_read_b32 v179, v47 offset:1240
	ds_read_b32 v180, v38 offset:1240
	ds_read_b32 v181, v35 offset:1240
	ds_read_b32 v182, v34 offset:1240
	ds_read_b32 v183, v40 offset:1240
	s_waitcnt lgkmcnt(11)
	v_mfma_f32_16x16x32_bf16 v[166:169], v[150:153], v[4:7], 0
	s_waitcnt lgkmcnt(10)
	v_mfma_f32_16x16x32_bf16 v[166:169], v[154:157], v[0:3], v[166:169]
	s_waitcnt lgkmcnt(9)
	v_mfma_f32_16x16x32_bf16 v[170:173], v[158:161], v[4:7], 0
	s_waitcnt lgkmcnt(8)
	v_mfma_f32_16x16x32_bf16 v[170:173], v[162:165], v[0:3], v[170:173]
	s_waitcnt lgkmcnt(0)
; #define LAS __attribute__((address_space(3)))
; __device__ __forceinline__ f32x4 mfma16(bf16x8 a, bf16x8 b, f32x4 c) { return __builtin_amdgcn_mfma_f32_16x16x32_bf16(a, b, c, 0, 0, 0); }
; template <bool CTXQ>
; __device__ __forceinline__ void attn_super(const bf16_t* QO, bf16_t* OO, const bf16_t* Kb, const bf16_t* VT, const float* rpb, LAS unsigned char* lds, int tid_, int lane_, int wave, int st) {
;     ...
;     for (int grp = G0; grp < 16; ++grp) {
;         const int tb = grp < 8 ? (krl0 + grp) * 64 + ks : 576 + 32 * (grp - 8);
; #pragma unroll
;         for (int T = 0; T < 2; ++T) {
;             const LAS unsigned char* kp = lds + (tb + koff + 4 * T) * AT_PITCH + g * 16;
;             const bf16x8 kf0 = *(const LAS bf16x8*)kp, kf1 = *(const LAS bf16x8*)(kp + 64);
;             f32x4 s = {0.f, 0.f, 0.f, 0.f};
;             s = mfma16(kf0, qf0, s); s = mfma16(kf1, qf1, s);
;             if (grp < 8) {
; #pragma unroll
;                 for (int j = 0; j < 4; ++j) s[j] += bptr[T][j][grp * 31] + madd[T][j];
;             }
;             S[grp][T] = s;
;         }
;         __builtin_amdgcn_sched_barrier(0);
;     }
	v_add_f32_e32 v176, v42, v176
	v_add_f32_e32 v177, v44, v177
	v_add_f32_e32 v178, v46, v178
	v_add_f32_e32 v179, v50, v179
	v_add_f32_e32 v180, v39, v180
	v_add_f32_e32 v181, v37, v181
	v_add_f32_e32 v182, v36, v182
	v_add_f32_e32 v183, v33, v183
	v_add_f32_e32 v31, v166, v176
	v_add_f32_e32 v108, v167, v177
	v_add_f32_e32 v110, v168, v178
	v_add_f32_e32 v111, v169, v179
	v_add_f32_e32 v112, v170, v180
	v_add_f32_e32 v113, v171, v181
	v_add_f32_e32 v114, v172, v182
	v_add_f32_e32 v117, v173, v183
	v_add_u32_e32 v51, s50, v32
	v_mad_u32_u24 v51, v51, v206, v205
	v_add_u32_e32 v207, 0x10400, v51
	ds_read_b128 v[150:153], v51
	ds_read_b128 v[154:157], v51 offset:64
	ds_read_b128 v[158:161], v207
	ds_read_b128 v[162:165], v207 offset:64
	ds_read_b32 v176, v41 offset:1364
	ds_read_b32 v177, v43 offset:1364
	ds_read_b32 v178, v45 offset:1364
	ds_read_b32 v179, v47 offset:1364
	ds_read_b32 v180, v38 offset:1364
	ds_read_b32 v181, v35 offset:1364
	ds_read_b32 v182, v34 offset:1364
	ds_read_b32 v183, v40 offset:1364
	s_waitcnt lgkmcnt(11)
	v_mfma_f32_16x16x32_bf16 v[166:169], v[150:153], v[4:7], 0
	s_waitcnt lgkmcnt(10)
	v_mfma_f32_16x16x32_bf16 v[166:169], v[154:157], v[0:3], v[166:169]
	s_waitcnt lgkmcnt(9)
	v_mfma_f32_16x16x32_bf16 v[170:173], v[158:161], v[4:7], 0
	s_waitcnt lgkmcnt(8)
	v_mfma_f32_16x16x32_bf16 v[170:173], v[162:165], v[0:3], v[170:173]
	s_waitcnt lgkmcnt(0)
	v_add_f32_e32 v176, v42, v176
	v_add_f32_e32 v177, v44, v177
	v_add_f32_e32 v178, v46, v178
	v_add_f32_e32 v179, v50, v179
	v_add_f32_e32 v180, v39, v180
	v_add_f32_e32 v181, v37, v181
	v_add_f32_e32 v182, v36, v182
	v_add_f32_e32 v183, v33, v183
	v_add_f32_e32 v115, v166, v176
	v_add_f32_e32 v116, v167, v177
	v_add_f32_e32 v118, v168, v178
	v_add_f32_e32 v119, v169, v179
	v_add_f32_e32 v120, v170, v180
	v_add_f32_e32 v121, v171, v181
	v_add_f32_e32 v122, v172, v182
	v_add_f32_e32 v125, v173, v183
	v_add_u32_e32 v51, s54, v32
	v_mad_u32_u24 v51, v51, v206, v205
	v_add_u32_e32 v207, 0x10400, v51
	ds_read_b128 v[150:153], v51
	ds_read_b128 v[154:157], v51 offset:64
	ds_read_b128 v[158:161], v207
	ds_read_b128 v[162:165], v207 offset:64
	ds_read_b32 v176, v41 offset:1488
	ds_read_b32 v177, v43 offset:1488
	ds_read_b32 v178, v45 offset:1488
	ds_read_b32 v179, v47 offset:1488
	ds_read_b32 v180, v38 offset:1488
	ds_read_b32 v181, v35 offset:1488
	ds_read_b32 v182, v34 offset:1488
	ds_read_b32 v183, v40 offset:1488
	s_waitcnt lgkmcnt(11)
	v_mfma_f32_16x16x32_bf16 v[166:169], v[150:153], v[4:7], 0
	s_waitcnt lgkmcnt(10)
	v_mfma_f32_16x16x32_bf16 v[166:169], v[154:157], v[0:3], v[166:169]
	s_waitcnt lgkmcnt(9)
	v_mfma_f32_16x16x32_bf16 v[170:173], v[158:161], v[4:7], 0
	s_waitcnt lgkmcnt(8)
	v_mfma_f32_16x16x32_bf16 v[170:173], v[162:165], v[0:3], v[170:173]
	s_waitcnt lgkmcnt(0)
	v_add_f32_e32 v176, v42, v176
	v_add_f32_e32 v177, v44, v177
	v_add_f32_e32 v178, v46, v178
	v_add_f32_e32 v179, v50, v179
	v_add_f32_e32 v180, v39, v180
	v_add_f32_e32 v181, v37, v181
	v_add_f32_e32 v182, v36, v182
	v_add_f32_e32 v183, v33, v183
	v_add_f32_e32 v123, v166, v176
	v_add_f32_e32 v124, v167, v177
	v_add_f32_e32 v126, v168, v178
	v_add_f32_e32 v127, v169, v179
	v_add_f32_e32 v128, v170, v180
	v_add_f32_e32 v129, v171, v181
	v_add_f32_e32 v130, v172, v182
	v_add_f32_e32 v133, v173, v183
	v_add_u32_e32 v51, s56, v32
	v_mad_u32_u24 v51, v51, v206, v205
	v_add_u32_e32 v207, 0x10400, v51
	ds_read_b128 v[150:153], v51
	ds_read_b128 v[154:157], v51 offset:64
	ds_read_b128 v[158:161], v207
	ds_read_b128 v[162:165], v207 offset:64
	ds_read_b32 v176, v41 offset:1612
	ds_read_b32 v177, v43 offset:1612
	ds_read_b32 v178, v45 offset:1612
	ds_read_b32 v179, v47 offset:1612
	ds_read_b32 v180, v38 offset:1612
	ds_read_b32 v181, v35 offset:1612
	ds_read_b32 v182, v34 offset:1612
	ds_read_b32 v183, v40 offset:1612
	s_waitcnt lgkmcnt(11)
	v_mfma_f32_16x16x32_bf16 v[166:169], v[150:153], v[4:7], 0
	s_waitcnt lgkmcnt(10)
	v_mfma_f32_16x16x32_bf16 v[166:169], v[154:157], v[0:3], v[166:169]
	s_waitcnt lgkmcnt(9)
	v_mfma_f32_16x16x32_bf16 v[170:173], v[158:161], v[4:7], 0
	s_waitcnt lgkmcnt(8)
	v_mfma_f32_16x16x32_bf16 v[170:173], v[162:165], v[0:3], v[170:173]
	s_waitcnt lgkmcnt(0)
	v_add_f32_e32 v176, v42, v176
	v_add_f32_e32 v177, v44, v177
	v_add_f32_e32 v178, v46, v178
	v_add_f32_e32 v179, v50, v179
	v_add_f32_e32 v180, v39, v180
	v_add_f32_e32 v181, v37, v181
	v_add_f32_e32 v182, v36, v182
	v_add_f32_e32 v183, v33, v183
	v_add_f32_e32 v131, v166, v176
	v_add_f32_e32 v132, v167, v177
	v_add_f32_e32 v134, v168, v178
	v_add_f32_e32 v135, v169, v179
	v_add_f32_e32 v136, v170, v180
	v_add_f32_e32 v137, v171, v181
	v_add_f32_e32 v138, v172, v182
	v_add_f32_e32 v141, v173, v183
	v_add_u32_e32 v51, s59, v32
	v_mad_u32_u24 v51, v51, v206, v205
	v_add_u32_e32 v207, 0x10400, v51
	ds_read_b128 v[150:153], v51
	ds_read_b128 v[154:157], v51 offset:64
	ds_read_b128 v[158:161], v207
	ds_read_b128 v[162:165], v207 offset:64
	ds_read_b32 v176, v41 offset:1736
	ds_read_b32 v177, v43 offset:1736
	ds_read_b32 v178, v45 offset:1736
	ds_read_b32 v179, v47 offset:1736
	ds_read_b32 v180, v38 offset:1736
	ds_read_b32 v181, v35 offset:1736
	ds_read_b32 v182, v34 offset:1736
	ds_read_b32 v183, v40 offset:1736
	s_waitcnt lgkmcnt(11)
	v_mfma_f32_16x16x32_bf16 v[166:169], v[150:153], v[4:7], 0
	s_waitcnt lgkmcnt(10)
	v_mfma_f32_16x16x32_bf16 v[166:169], v[154:157], v[0:3], v[166:169]
	s_waitcnt lgkmcnt(9)
	v_mfma_f32_16x16x32_bf16 v[170:173], v[158:161], v[4:7], 0
	s_waitcnt lgkmcnt(8)
	v_mfma_f32_16x16x32_bf16 v[170:173], v[162:165], v[0:3], v[170:173]
	s_waitcnt lgkmcnt(0)
; #define LAS __attribute__((address_space(3)))
; __device__ __forceinline__ f32x4 mfma16(bf16x8 a, bf16x8 b, f32x4 c) { return __builtin_amdgcn_mfma_f32_16x16x32_bf16(a, b, c, 0, 0, 0); }
; template <bool CTXQ>
; __device__ __forceinline__ void attn_super(const bf16_t* QO, bf16_t* OO, const bf16_t* Kb, const bf16_t* VT, const float* rpb, LAS unsigned char* lds, int tid_, int lane_, int wave, int st) {
;     ...
;     for (int grp = G0; grp < 16; ++grp) {
;         const int tb = grp < 8 ? (krl0 + grp) * 64 + ks : 576 + 32 * (grp - 8);
; #pragma unroll
;         for (int T = 0; T < 2; ++T) {
;             const LAS unsigned char* kp = lds + (tb + koff + 4 * T) * AT_PITCH + g * 16;
;             const bf16x8 kf0 = *(const LAS bf16x8*)kp, kf1 = *(const LAS bf16x8*)(kp + 64);
;             f32x4 s = {0.f, 0.f, 0.f, 0.f};
;             s = mfma16(kf0, qf0, s); s = mfma16(kf1, qf1, s);
;             if (grp < 8) {
; #pragma unroll
;                 for (int j = 0; j < 4; ++j) s[j] += bptr[T][j][grp * 31] + madd[T][j];
;             }
;             S[grp][T] = s;
;         }
;         __builtin_amdgcn_sched_barrier(0);
;     }
	v_add_f32_e32 v176, v42, v176
	v_add_f32_e32 v177, v44, v177
	v_add_f32_e32 v178, v46, v178
	v_add_f32_e32 v179, v50, v179
	v_add_f32_e32 v180, v39, v180
	v_add_f32_e32 v181, v37, v181
	v_add_f32_e32 v182, v36, v182
	v_add_f32_e32 v183, v33, v183
	v_add_f32_e32 v139, v166, v176
	v_add_f32_e32 v140, v167, v177
	v_add_f32_e32 v142, v168, v178
	v_add_f32_e32 v143, v169, v179
	v_add_f32_e32 v144, v170, v180
	v_add_f32_e32 v145, v171, v181
	v_add_f32_e32 v146, v172, v182
	v_add_f32_e32 v147, v173, v183
	v_mad_u32_u24 v106, v99, v208, v209
	v_add_u32_e32 v32, 0xb400, v106
	ds_read_b128 v[32:35], v32
	v_add_u32_e32 v36, 0xb440, v106
	ds_read_b128 v[36:39], v36
	v_add_u32_e32 v40, 0x1b840, v106
	s_waitcnt lgkmcnt(1)
	v_mfma_f32_16x16x32_bf16 v[32:35], v[32:35], v[4:7], 0
	ds_read_b128 v[40:43], v40
	s_waitcnt lgkmcnt(1)
	v_mfma_f32_16x16x32_bf16 v[32:35], v[36:39], v[0:3], v[32:35]
	v_add_u32_e32 v36, 0x1b800, v106
	ds_read_b128 v[36:39], v36
	s_waitcnt lgkmcnt(0)
	v_mfma_f32_16x16x32_bf16 v[36:39], v[36:39], v[4:7], 0
	v_mfma_f32_16x16x32_bf16 v[94:97], v[40:43], v[0:3], v[36:39]
	s_nop 6
	v_add_u32_e32 v36, 0xbe00, v106
	ds_read_b128 v[36:39], v36
	v_add_u32_e32 v40, 0xbe40, v106
	ds_read_b128 v[40:43], v40
	v_add_u32_e32 v44, 0x1c240, v106
	s_waitcnt lgkmcnt(1)
	v_mfma_f32_16x16x32_bf16 v[36:39], v[36:39], v[4:7], 0
	ds_read_b128 v[44:47], v44
	s_waitcnt lgkmcnt(1)
	v_mfma_f32_16x16x32_bf16 v[36:39], v[40:43], v[0:3], v[36:39]
	v_add_u32_e32 v40, 0x1c200, v106
	ds_read_b128 v[40:43], v40
	s_waitcnt lgkmcnt(0)
	v_mfma_f32_16x16x32_bf16 v[40:43], v[40:43], v[4:7], 0
	v_mfma_f32_16x16x32_bf16 v[90:93], v[44:47], v[0:3], v[40:43]
	s_nop 6
	v_add_u32_e32 v40, 0xc800, v106
	ds_read_b128 v[40:43], v40
	v_add_u32_e32 v44, 0xc840, v106
	ds_read_b128 v[44:47], v44
	v_add_u32_e32 v50, 0x1cc40, v106
	s_waitcnt lgkmcnt(1)
	v_mfma_f32_16x16x32_bf16 v[40:43], v[40:43], v[4:7], 0
	ds_read_b128 v[50:53], v50
	s_waitcnt lgkmcnt(1)
	v_mfma_f32_16x16x32_bf16 v[40:43], v[44:47], v[0:3], v[40:43]
	v_add_u32_e32 v44, 0x1cc00, v106
	ds_read_b128 v[44:47], v44
	s_waitcnt lgkmcnt(0)
	v_mfma_f32_16x16x32_bf16 v[44:47], v[44:47], v[4:7], 0
	v_mfma_f32_16x16x32_bf16 v[86:89], v[50:53], v[0:3], v[44:47]
	s_nop 6
	v_add_u32_e32 v44, 0xd200, v106
	ds_read_b128 v[44:47], v44
	v_add_u32_e32 v50, 0xd240, v106
	ds_read_b128 v[50:53], v50
	v_add_u32_e32 v54, 0x1d640, v106
	s_waitcnt lgkmcnt(1)
	v_mfma_f32_16x16x32_bf16 v[44:47], v[44:47], v[4:7], 0
	ds_read_b128 v[54:57], v54
	s_waitcnt lgkmcnt(1)
	v_mfma_f32_16x16x32_bf16 v[44:47], v[50:53], v[0:3], v[44:47]
	v_add_u32_e32 v50, 0x1d600, v106
	ds_read_b128 v[50:53], v50
	s_waitcnt lgkmcnt(0)
	v_mfma_f32_16x16x32_bf16 v[50:53], v[50:53], v[4:7], 0
	v_mfma_f32_16x16x32_bf16 v[82:85], v[54:57], v[0:3], v[50:53]
	s_nop 6
	v_add_u32_e32 v50, 0xdc00, v106
	ds_read_b128 v[50:53], v50
	v_add_u32_e32 v54, 0xdc40, v106
	ds_read_b128 v[54:57], v54
	v_add_u32_e32 v58, 0x1e040, v106
	s_waitcnt lgkmcnt(1)
	v_mfma_f32_16x16x32_bf16 v[50:53], v[50:53], v[4:7], 0
	ds_read_b128 v[58:61], v58
	s_waitcnt lgkmcnt(1)
	v_mfma_f32_16x16x32_bf16 v[50:53], v[54:57], v[0:3], v[50:53]
	v_add_u32_e32 v54, 0x1e000, v106
	ds_read_b128 v[54:57], v54
	s_waitcnt lgkmcnt(0)
	v_mfma_f32_16x16x32_bf16 v[54:57], v[54:57], v[4:7], 0
	v_mfma_f32_16x16x32_bf16 v[78:81], v[58:61], v[0:3], v[54:57]
	s_nop 6
	v_add_u32_e32 v54, 0xe600, v106
	ds_read_b128 v[54:57], v54
	v_add_u32_e32 v58, 0xe640, v106
	ds_read_b128 v[58:61], v58
	v_add_u32_e32 v62, 0x1ea40, v106
	s_waitcnt lgkmcnt(1)
	v_mfma_f32_16x16x32_bf16 v[54:57], v[54:57], v[4:7], 0
	ds_read_b128 v[62:65], v62
	s_waitcnt lgkmcnt(1)
	v_mfma_f32_16x16x32_bf16 v[54:57], v[58:61], v[0:3], v[54:57]
	v_add_u32_e32 v58, 0x1ea00, v106
	ds_read_b128 v[58:61], v58
	s_waitcnt lgkmcnt(0)
	v_mfma_f32_16x16x32_bf16 v[58:61], v[58:61], v[4:7], 0
	v_mfma_f32_16x16x32_bf16 v[70:73], v[62:65], v[0:3], v[58:61]
	s_nop 6
	v_add_u32_e32 v58, 0xf000, v106
	ds_read_b128 v[58:61], v58
	v_add_u32_e32 v62, 0xf040, v106
	ds_read_b128 v[62:65], v62
	v_add_u32_e32 v66, 0x1f440, v106
	s_waitcnt lgkmcnt(1)
	v_mfma_f32_16x16x32_bf16 v[58:61], v[58:61], v[4:7], 0
	ds_read_b128 v[66:69], v66
	s_waitcnt lgkmcnt(1)
	v_mfma_f32_16x16x32_bf16 v[58:61], v[62:65], v[0:3], v[58:61]
	v_add_u32_e32 v62, 0x1f400, v106
	ds_read_b128 v[62:65], v62
	s_waitcnt lgkmcnt(0)
	v_mfma_f32_16x16x32_bf16 v[62:65], v[62:65], v[4:7], 0
	v_mfma_f32_16x16x32_bf16 v[62:65], v[66:69], v[0:3], v[62:65]
	v_add_u32_e32 v66, 0xfa00, v106
	v_add_u32_e32 v74, 0x1fe00, v106
	ds_read_b128 v[66:69], v66
	ds_read_b128 v[74:77], v74
	v_add_u32_e32 v107, 0xfa40, v106
	v_add_u32_e32 v106, 0x1fe40, v106
	s_waitcnt lgkmcnt(1)
	v_mfma_f32_16x16x32_bf16 v[66:69], v[66:69], v[4:7], 0
	s_waitcnt lgkmcnt(0)
	v_mfma_f32_16x16x32_bf16 v[4:7], v[74:77], v[4:7], 0
	ds_read_b128 v[74:77], v107
	s_waitcnt lgkmcnt(0)
	v_mfma_f32_16x16x32_bf16 v[74:77], v[74:77], v[0:3], v[66:69]
	s_nop 2
	ds_read_b128 v[66:69], v106
	s_waitcnt lgkmcnt(0)
	v_mfma_f32_16x16x32_bf16 v[66:69], v[66:69], v[0:3], v[4:7]
	v_max_f32_e32 v0, v17, v16
	v_max_f32_e32 v1, v11, v10
	v_max3_f32 v0, v19, v18, v0
	v_max3_f32 v1, v15, v13, v1
	s_mov_b32 s2, 0xf149f2ca
	v_max3_f32 v0, v0, s2, v1
	v_max_f32_e32 v1, v12, v14
	v_max_f32_e32 v2, v22, v25
	v_max3_f32 v1, v8, v9, v1
	v_max3_f32 v2, v20, v21, v2
	v_max3_f32 v0, v0, v1, v2
	v_max_f32_e32 v1, v26, v27
	v_max_f32_e32 v2, v30, v109
	v_max3_f32 v1, v23, v24, v1
	v_max3_f32 v2, v28, v29, v2
	v_max3_f32 v0, v0, v1, v2
	v_max_f32_e32 v1, v110, v111
	v_max_f32_e32 v2, v114, v117
	v_max3_f32 v1, v31, v108, v1
	v_max3_f32 v2, v112, v113, v2
	v_max3_f32 v0, v0, v1, v2
	v_max_f32_e32 v1, v118, v119
	v_max_f32_e32 v2, v122, v125
	v_max3_f32 v1, v115, v116, v1
	v_max3_f32 v2, v120, v121, v2
	v_max3_f32 v0, v0, v1, v2
	v_max_f32_e32 v1, v126, v127
	v_max_f32_e32 v2, v130, v133
	v_max3_f32 v1, v123, v124, v1
	v_max3_f32 v2, v128, v129, v2
	v_max3_f32 v0, v0, v1, v2
	v_max_f32_e32 v1, v134, v135
	v_max_f32_e32 v2, v138, v141
	v_max3_f32 v1, v131, v132, v1
	v_max3_f32 v2, v136, v137, v2
	v_max3_f32 v0, v0, v1, v2
	v_max_f32_e32 v1, v142, v143
	v_max_f32_e32 v2, v146, v147
	v_max3_f32 v1, v139, v140, v1
	v_max3_f32 v2, v144, v145, v2
	v_max3_f32 v0, v0, v1, v2
	v_max_f32_e32 v1, v35, v35
	v_max_f32_e32 v2, v34, v34
	v_max_f32_e32 v1, v2, v1
	v_max_f32_e32 v2, v97, v97
	v_max_f32_e32 v3, v96, v96
	v_max_f32_e32 v2, v3, v2
	v_max3_f32 v1, v32, v33, v1
	v_max3_f32 v2, v94, v95, v2
	v_max3_f32 v0, v0, v1, v2
	v_max_f32_e32 v1, v39, v39
	v_max_f32_e32 v2, v38, v38
	v_max_f32_e32 v1, v2, v1
	v_max_f32_e32 v2, v93, v93
	v_max_f32_e32 v3, v92, v92
	v_max_f32_e32 v2, v3, v2
	v_max3_f32 v1, v36, v37, v1
	v_max3_f32 v2, v90, v91, v2
	v_max3_f32 v0, v0, v1, v2
	v_max_f32_e32 v1, v43, v43
	v_max_f32_e32 v2, v42, v42
	v_max_f32_e32 v1, v2, v1
	v_max_f32_e32 v2, v89, v89
	v_max_f32_e32 v3, v88, v88
	v_max_f32_e32 v2, v3, v2
	v_max3_f32 v1, v40, v41, v1
	v_max3_f32 v2, v86, v87, v2
	v_max3_f32 v0, v0, v1, v2
	v_max_f32_e32 v1, v47, v47
	v_max_f32_e32 v2, v46, v46
	v_max_f32_e32 v1, v2, v1
	v_max_f32_e32 v2, v85, v85
	v_max_f32_e32 v3, v84, v84
	v_max_f32_e32 v2, v3, v2
	v_max3_f32 v1, v44, v45, v1
	v_max3_f32 v2, v82, v83, v2
	v_max3_f32 v0, v0, v1, v2
	v_max_f32_e32 v1, v53, v53
	v_max_f32_e32 v2, v52, v52
	v_max_f32_e32 v1, v2, v1
	v_max_f32_e32 v2, v81, v81
	v_max_f32_e32 v3, v80, v80
	v_max_f32_e32 v2, v3, v2
	v_max3_f32 v1, v50, v51, v1
	v_max3_f32 v2, v78, v79, v2
	v_max3_f32 v0, v0, v1, v2
	v_max_f32_e32 v1, v57, v57
	v_max_f32_e32 v2, v56, v56
	v_max_f32_e32 v1, v2, v1
	v_max_f32_e32 v2, v73, v73
	v_max_f32_e32 v3, v72, v72
	v_max_f32_e32 v2, v3, v2
	v_max3_f32 v1, v54, v55, v1
	v_max3_f32 v2, v70, v71, v2
	v_max3_f32 v0, v0, v1, v2
	v_max_f32_e32 v1, v61, v61
	v_max_f32_e32 v2, v60, v60
	v_max_f32_e32 v1, v2, v1
	v_max_f32_e32 v2, v65, v65
	v_max_f32_e32 v3, v64, v64
	v_max_f32_e32 v2, v3, v2
	v_max3_f32 v1, v58, v59, v1
	v_max3_f32 v2, v62, v63, v2
	v_max3_f32 v0, v0, v1, v2
	v_max_f32_e32 v1, v77, v77
	v_max_f32_e32 v2, v76, v76
	v_max_f32_e32 v1, v2, v1
	v_max_f32_e32 v2, v69, v69
	v_max_f32_e32 v3, v68, v68
	v_max_f32_e32 v2, v3, v2
	v_max3_f32 v1, v74, v75, v1
	v_max3_f32 v2, v66, v67, v2
	v_max3_f32 v0, v0, v1, v2
	v_xor_b32_e32 v1, 16, v222
	v_cmp_lt_i32_e32 vcc, v1, v227
	s_barrier
	s_nop 0
	v_cndmask_b32_e32 v1, v222, v1, vcc
	v_lshlrev_b32_e32 v106, 2, v1
	ds_bpermute_b32 v1, v106, v0
	v_cmp_lt_i32_e32 vcc, v226, v227
	s_waitcnt lgkmcnt(0)
	v_max_f32_e32 v1, v1, v1
	v_max_f32_e32 v0, v0, v1
	v_cndmask_b32_e32 v1, v222, v226, vcc
	v_lshlrev_b32_e32 v107, 2, v1
	ds_bpermute_b32 v1, v107, v0
	s_waitcnt lgkmcnt(0)
	v_max_f32_e32 v1, v1, v1
	v_max_f32_e32 v148, v0, v1
	v_sub_f32_e32 v0, v19, v148
	v_exp_f32_e32 v0, v0
	v_sub_f32_e32 v1, v18, v148
	v_exp_f32_e32 v1, v1
	v_sub_f32_e32 v2, v17, v148
	v_exp_f32_e32 v2, v2
	v_sub_f32_e32 v3, v16, v148
	v_exp_f32_e32 v3, v3
	v_sub_f32_e32 v5, v15, v148
	v_add_f32_e32 v4, 0, v0
	v_exp_f32_e32 v6, v5
	v_sub_f32_e32 v5, v13, v148
	v_add_f32_e32 v4, v1, v4
	v_exp_f32_e32 v7, v5
	v_sub_f32_e32 v5, v11, v148
	v_add_f32_e32 v4, v2, v4
	v_exp_f32_e32 v11, v5
	v_sub_f32_e32 v5, v10, v148
	v_add_f32_e32 v4, v3, v4
	v_exp_f32_e32 v10, v5
	v_add_f32_e32 v4, v6, v4
	v_add_f32_e32 v4, v7, v4
	v_add_f32_e32 v4, v11, v4
	v_add_f32_e32 v13, v10, v4
	v_cvt_pk_bf16_f32 v4, v0, v1
	v_cvt_pk_bf16_f32 v5, v2, v3
	v_cvt_pk_bf16_f32 v6, v6, v7
	v_cvt_pk_bf16_f32 v7, v11, v10
	v_sub_f32_e32 v0, v8, v148
	v_exp_f32_e32 v0, v0
	v_sub_f32_e32 v1, v9, v148
	v_exp_f32_e32 v1, v1
	v_sub_f32_e32 v2, v12, v148
	v_exp_f32_e32 v2, v2
	v_sub_f32_e32 v3, v14, v148
	v_exp_f32_e32 v3, v3
	v_sub_f32_e32 v9, v20, v148
	v_add_f32_e32 v8, v0, v13
	v_exp_f32_e32 v9, v9
	v_sub_f32_e32 v10, v21, v148
	v_add_f32_e32 v8, v1, v8
	v_exp_f32_e32 v10, v10
	v_sub_f32_e32 v11, v22, v148
	v_add_f32_e32 v8, v2, v8
	v_exp_f32_e32 v11, v11
	v_sub_f32_e32 v12, v25, v148
	v_add_f32_e32 v8, v3, v8
	v_exp_f32_e32 v12, v12
	v_add_f32_e32 v8, v9, v8
	v_add_f32_e32 v8, v10, v8
	v_add_f32_e32 v8, v11, v8
	v_add_f32_e32 v8, v12, v8
	v_cvt_pk_bf16_f32 v0, v0, v1
	v_cvt_pk_bf16_f32 v1, v2, v3
	v_cvt_pk_bf16_f32 v2, v9, v10
	v_cvt_pk_bf16_f32 v3, v11, v12
	v_sub_f32_e32 v9, v23, v148
	v_exp_f32_e32 v9, v9
	v_sub_f32_e32 v10, v24, v148
	v_exp_f32_e32 v10, v10
	v_sub_f32_e32 v11, v26, v148
	v_exp_f32_e32 v11, v11
	v_sub_f32_e32 v12, v27, v148
	v_exp_f32_e32 v12, v12
	v_sub_f32_e32 v13, v28, v148
	v_add_f32_e32 v8, v9, v8
	v_exp_f32_e32 v13, v13
	v_sub_f32_e32 v14, v29, v148
	v_add_f32_e32 v8, v10, v8
	v_exp_f32_e32 v14, v14
	v_sub_f32_e32 v15, v30, v148
	v_add_f32_e32 v8, v11, v8
	v_exp_f32_e32 v15, v15
	v_sub_f32_e32 v16, v109, v148
	v_add_f32_e32 v8, v12, v8
	v_exp_f32_e32 v16, v16
	v_add_f32_e32 v8, v13, v8
	v_add_f32_e32 v8, v14, v8
	v_add_f32_e32 v8, v15, v8
	v_add_f32_e32 v17, v16, v8
	v_cvt_pk_bf16_f32 v8, v9, v10
	v_cvt_pk_bf16_f32 v9, v11, v12
	v_cvt_pk_bf16_f32 v10, v13, v14
	v_cvt_pk_bf16_f32 v11, v15, v16
	v_sub_f32_e32 v12, v31, v148
	v_exp_f32_e32 v12, v12
	v_sub_f32_e32 v13, v108, v148
	v_exp_f32_e32 v13, v13
	v_sub_f32_e32 v14, v110, v148
	v_exp_f32_e32 v14, v14
	v_sub_f32_e32 v15, v111, v148
	v_exp_f32_e32 v15, v15
	v_add_f32_e32 v16, v12, v17
	v_sub_f32_e32 v17, v112, v148
	v_exp_f32_e32 v17, v17
	v_sub_f32_e32 v18, v113, v148
	v_add_f32_e32 v16, v13, v16
	v_exp_f32_e32 v18, v18
	v_sub_f32_e32 v19, v114, v148
	v_add_f32_e32 v16, v14, v16
	v_exp_f32_e32 v19, v19
	v_sub_f32_e32 v20, v117, v148
	v_add_f32_e32 v16, v15, v16
	v_exp_f32_e32 v20, v20
	v_add_f32_e32 v16, v17, v16
	v_add_f32_e32 v16, v18, v16
	v_add_f32_e32 v16, v19, v16
	v_add_f32_e32 v16, v20, v16
	v_cvt_pk_bf16_f32 v12, v12, v13
	v_cvt_pk_bf16_f32 v13, v14, v15
	v_cvt_pk_bf16_f32 v14, v17, v18
	v_cvt_pk_bf16_f32 v15, v19, v20
	v_sub_f32_e32 v17, v115, v148
	v_exp_f32_e32 v17, v17
	v_sub_f32_e32 v18, v116, v148
	v_exp_f32_e32 v18, v18
	v_sub_f32_e32 v19, v118, v148
	v_exp_f32_e32 v19, v19
	v_sub_f32_e32 v20, v119, v148
	v_exp_f32_e32 v20, v20
	v_sub_f32_e32 v21, v120, v148
	v_add_f32_e32 v16, v17, v16
	v_exp_f32_e32 v21, v21
	v_sub_f32_e32 v22, v121, v148
	v_add_f32_e32 v16, v18, v16
	v_exp_f32_e32 v22, v22
	v_sub_f32_e32 v23, v122, v148
	v_add_f32_e32 v16, v19, v16
	v_exp_f32_e32 v23, v23
	v_sub_f32_e32 v24, v125, v148
	v_add_f32_e32 v16, v20, v16
	v_exp_f32_e32 v24, v24
	v_add_f32_e32 v16, v21, v16
	v_add_f32_e32 v16, v22, v16
	v_add_f32_e32 v16, v23, v16
	v_add_f32_e32 v25, v24, v16
	v_cvt_pk_bf16_f32 v16, v17, v18
	v_cvt_pk_bf16_f32 v17, v19, v20
	v_cvt_pk_bf16_f32 v18, v21, v22
	v_cvt_pk_bf16_f32 v19, v23, v24
	v_sub_f32_e32 v20, v123, v148
	v_exp_f32_e32 v20, v20
	v_sub_f32_e32 v21, v124, v148
	v_exp_f32_e32 v21, v21
	v_sub_f32_e32 v22, v126, v148
	v_exp_f32_e32 v22, v22
	v_sub_f32_e32 v23, v127, v148
	v_exp_f32_e32 v23, v23
	v_add_f32_e32 v24, v20, v25
	v_sub_f32_e32 v25, v128, v148
	v_exp_f32_e32 v25, v25
	v_sub_f32_e32 v26, v129, v148
	v_add_f32_e32 v24, v21, v24
	v_exp_f32_e32 v26, v26
	v_sub_f32_e32 v27, v130, v148
	v_add_f32_e32 v24, v22, v24
	v_exp_f32_e32 v27, v27
	v_sub_f32_e32 v28, v133, v148
	v_add_f32_e32 v24, v23, v24
	v_exp_f32_e32 v28, v28
	v_add_f32_e32 v24, v25, v24
	v_add_f32_e32 v24, v26, v24
	v_add_f32_e32 v24, v27, v24
	v_add_f32_e32 v24, v28, v24
	v_cvt_pk_bf16_f32 v20, v20, v21
	v_cvt_pk_bf16_f32 v21, v22, v23
	v_cvt_pk_bf16_f32 v22, v25, v26
	v_cvt_pk_bf16_f32 v23, v27, v28
	v_sub_f32_e32 v25, v131, v148
	v_exp_f32_e32 v25, v25
	v_sub_f32_e32 v26, v132, v148
	v_exp_f32_e32 v26, v26
	v_sub_f32_e32 v27, v134, v148
	v_exp_f32_e32 v27, v27
	v_sub_f32_e32 v28, v135, v148
	v_exp_f32_e32 v28, v28
	v_sub_f32_e32 v29, v136, v148
	v_add_f32_e32 v24, v25, v24
	v_exp_f32_e32 v29, v29
	v_sub_f32_e32 v30, v137, v148
	v_add_f32_e32 v24, v26, v24
	v_exp_f32_e32 v30, v30
	v_sub_f32_e32 v31, v138, v148
	v_add_f32_e32 v24, v27, v24
	v_exp_f32_e32 v31, v31
	v_sub_f32_e32 v108, v141, v148
	v_add_f32_e32 v24, v28, v24
	v_exp_f32_e32 v108, v108
	v_add_f32_e32 v24, v29, v24
	v_add_f32_e32 v24, v30, v24
	v_add_f32_e32 v24, v31, v24
	v_add_f32_e32 v109, v108, v24
	v_cvt_pk_bf16_f32 v24, v25, v26
	v_cvt_pk_bf16_f32 v25, v27, v28
	v_cvt_pk_bf16_f32 v26, v29, v30
	v_cvt_pk_bf16_f32 v27, v31, v108
	v_sub_f32_e32 v28, v139, v148
	v_exp_f32_e32 v28, v28
	v_sub_f32_e32 v29, v140, v148
	v_exp_f32_e32 v29, v29
	v_sub_f32_e32 v30, v142, v148
	v_exp_f32_e32 v30, v30
	v_sub_f32_e32 v31, v143, v148
	v_exp_f32_e32 v31, v31
	v_add_f32_e32 v108, v28, v109
	v_sub_f32_e32 v109, v144, v148
	v_exp_f32_e32 v109, v109
	v_sub_f32_e32 v110, v145, v148
	v_add_f32_e32 v108, v29, v108
	v_exp_f32_e32 v110, v110
	v_sub_f32_e32 v111, v146, v148
	v_add_f32_e32 v108, v30, v108
	v_exp_f32_e32 v111, v111
	v_sub_f32_e32 v112, v147, v148
	v_add_f32_e32 v108, v31, v108
	v_exp_f32_e32 v112, v112
	v_add_f32_e32 v108, v109, v108
	v_add_f32_e32 v108, v110, v108
	v_add_f32_e32 v108, v111, v108
	v_add_f32_e32 v108, v112, v108
	v_cvt_pk_bf16_f32 v28, v28, v29
	v_cvt_pk_bf16_f32 v29, v30, v31
	v_cvt_pk_bf16_f32 v30, v109, v110
	v_cvt_pk_bf16_f32 v31, v111, v112
	v_sub_f32_e32 v32, v32, v148
	v_exp_f32_e32 v32, v32
	v_sub_f32_e32 v33, v33, v148
	v_exp_f32_e32 v33, v33
	v_sub_f32_e32 v34, v34, v148
	v_exp_f32_e32 v34, v34
	v_sub_f32_e32 v35, v35, v148
	v_exp_f32_e32 v35, v35
	v_sub_f32_e32 v94, v94, v148
	v_add_f32_e32 v108, v32, v108
	v_exp_f32_e32 v94, v94
	v_sub_f32_e32 v95, v95, v148
	v_add_f32_e32 v108, v33, v108
	v_exp_f32_e32 v95, v95
	v_sub_f32_e32 v96, v96, v148
	v_add_f32_e32 v108, v34, v108
	v_exp_f32_e32 v96, v96
	v_sub_f32_e32 v97, v97, v148
	v_add_f32_e32 v108, v35, v108
	v_exp_f32_e32 v97, v97
	v_add_f32_e32 v108, v94, v108
	v_add_f32_e32 v108, v95, v108
	v_add_f32_e32 v108, v96, v108
	v_add_f32_e32 v108, v97, v108
	v_cvt_pk_bf16_f32 v32, v32, v33
	v_cvt_pk_bf16_f32 v33, v34, v35
	v_cvt_pk_bf16_f32 v34, v94, v95
	v_cvt_pk_bf16_f32 v35, v96, v97
	v_sub_f32_e32 v36, v36, v148
	v_exp_f32_e32 v36, v36
	v_sub_f32_e32 v37, v37, v148
	v_exp_f32_e32 v37, v37
	v_sub_f32_e32 v38, v38, v148
	v_exp_f32_e32 v38, v38
	v_sub_f32_e32 v39, v39, v148
	v_exp_f32_e32 v39, v39
	v_sub_f32_e32 v90, v90, v148
	v_add_f32_e32 v94, v36, v108
	v_exp_f32_e32 v90, v90
	v_sub_f32_e32 v91, v91, v148
	v_add_f32_e32 v94, v37, v94
	v_exp_f32_e32 v91, v91
	v_sub_f32_e32 v92, v92, v148
	v_add_f32_e32 v94, v38, v94
	v_exp_f32_e32 v92, v92
	v_sub_f32_e32 v93, v93, v148
	v_add_f32_e32 v94, v39, v94
	v_exp_f32_e32 v93, v93
	v_add_f32_e32 v94, v90, v94
	v_add_f32_e32 v94, v91, v94
	v_add_f32_e32 v94, v92, v94
	v_add_f32_e32 v94, v93, v94
	v_cvt_pk_bf16_f32 v36, v36, v37
	v_cvt_pk_bf16_f32 v37, v38, v39
	v_cvt_pk_bf16_f32 v38, v90, v91
	v_cvt_pk_bf16_f32 v39, v92, v93
	v_sub_f32_e32 v40, v40, v148
	v_exp_f32_e32 v40, v40
	v_sub_f32_e32 v41, v41, v148
	v_exp_f32_e32 v41, v41
	v_sub_f32_e32 v42, v42, v148
	v_exp_f32_e32 v42, v42
	v_sub_f32_e32 v43, v43, v148
	v_exp_f32_e32 v43, v43
	v_sub_f32_e32 v86, v86, v148
	v_add_f32_e32 v90, v40, v94
	v_exp_f32_e32 v86, v86
	v_sub_f32_e32 v87, v87, v148
	v_add_f32_e32 v90, v41, v90
	v_exp_f32_e32 v87, v87
	v_sub_f32_e32 v88, v88, v148
	v_add_f32_e32 v90, v42, v90
	v_exp_f32_e32 v88, v88
	v_sub_f32_e32 v89, v89, v148
	v_add_f32_e32 v90, v43, v90
	v_exp_f32_e32 v89, v89
	v_add_f32_e32 v90, v86, v90
	v_add_f32_e32 v90, v87, v90
	v_add_f32_e32 v90, v88, v90
	v_add_f32_e32 v90, v89, v90
	v_cvt_pk_bf16_f32 v40, v40, v41
	v_cvt_pk_bf16_f32 v41, v42, v43
	v_cvt_pk_bf16_f32 v42, v86, v87
	v_cvt_pk_bf16_f32 v43, v88, v89
	v_sub_f32_e32 v44, v44, v148
	v_exp_f32_e32 v44, v44
	v_sub_f32_e32 v45, v45, v148
	v_exp_f32_e32 v45, v45
	v_sub_f32_e32 v46, v46, v148
	v_exp_f32_e32 v46, v46
	v_sub_f32_e32 v47, v47, v148
	v_exp_f32_e32 v47, v47
	v_sub_f32_e32 v82, v82, v148
	v_add_f32_e32 v86, v44, v90
	v_exp_f32_e32 v82, v82
	v_sub_f32_e32 v83, v83, v148
	v_add_f32_e32 v86, v45, v86
	v_exp_f32_e32 v83, v83
	v_sub_f32_e32 v84, v84, v148
	v_add_f32_e32 v86, v46, v86
	v_exp_f32_e32 v84, v84
	v_sub_f32_e32 v85, v85, v148
	v_add_f32_e32 v86, v47, v86
	v_exp_f32_e32 v85, v85
	v_add_f32_e32 v86, v82, v86
	v_add_f32_e32 v86, v83, v86
	v_add_f32_e32 v86, v84, v86
	v_add_f32_e32 v86, v85, v86
	v_cvt_pk_bf16_f32 v44, v44, v45
	v_cvt_pk_bf16_f32 v45, v46, v47
	v_cvt_pk_bf16_f32 v46, v82, v83
	v_cvt_pk_bf16_f32 v47, v84, v85
	v_sub_f32_e32 v50, v50, v148
	v_exp_f32_e32 v50, v50
	v_sub_f32_e32 v51, v51, v148
	v_exp_f32_e32 v51, v51
	v_sub_f32_e32 v52, v52, v148
	v_exp_f32_e32 v52, v52
	v_sub_f32_e32 v53, v53, v148
	v_exp_f32_e32 v53, v53
	v_sub_f32_e32 v78, v78, v148
	v_add_f32_e32 v82, v50, v86
	v_exp_f32_e32 v78, v78
	v_sub_f32_e32 v79, v79, v148
	v_add_f32_e32 v82, v51, v82
	v_exp_f32_e32 v79, v79
	v_sub_f32_e32 v80, v80, v148
	v_add_f32_e32 v82, v52, v82
	v_exp_f32_e32 v80, v80
	v_sub_f32_e32 v81, v81, v148
	v_add_f32_e32 v82, v53, v82
	v_exp_f32_e32 v81, v81
	v_add_f32_e32 v82, v78, v82
	v_add_f32_e32 v82, v79, v82
	v_add_f32_e32 v82, v80, v82
	v_add_f32_e32 v82, v81, v82
	v_cvt_pk_bf16_f32 v50, v50, v51
	v_cvt_pk_bf16_f32 v51, v52, v53
	v_cvt_pk_bf16_f32 v52, v78, v79
	v_cvt_pk_bf16_f32 v53, v80, v81
	v_sub_f32_e32 v54, v54, v148
	v_exp_f32_e32 v54, v54
	v_sub_f32_e32 v55, v55, v148
	v_exp_f32_e32 v55, v55
	v_sub_f32_e32 v56, v56, v148
	v_exp_f32_e32 v56, v56
	v_sub_f32_e32 v57, v57, v148
	v_exp_f32_e32 v57, v57
	v_sub_f32_e32 v70, v70, v148
	v_add_f32_e32 v78, v54, v82
	v_exp_f32_e32 v70, v70
	v_sub_f32_e32 v71, v71, v148
	v_add_f32_e32 v78, v55, v78
	v_exp_f32_e32 v71, v71
	v_sub_f32_e32 v72, v72, v148
	v_add_f32_e32 v78, v56, v78
	v_exp_f32_e32 v72, v72
	v_sub_f32_e32 v73, v73, v148
	v_add_f32_e32 v78, v57, v78
	v_exp_f32_e32 v73, v73
	v_add_f32_e32 v78, v70, v78
	v_add_f32_e32 v78, v71, v78
	v_add_f32_e32 v78, v72, v78
	v_add_f32_e32 v78, v73, v78
	v_cvt_pk_bf16_f32 v54, v54, v55
	v_cvt_pk_bf16_f32 v55, v56, v57
	v_cvt_pk_bf16_f32 v56, v70, v71
	v_cvt_pk_bf16_f32 v57, v72, v73
	v_sub_f32_e32 v58, v58, v148
	v_exp_f32_e32 v58, v58
	v_sub_f32_e32 v59, v59, v148
	v_exp_f32_e32 v59, v59
	v_sub_f32_e32 v60, v60, v148
	v_exp_f32_e32 v60, v60
	v_sub_f32_e32 v61, v61, v148
	v_exp_f32_e32 v61, v61
	v_sub_f32_e32 v62, v62, v148
	v_add_f32_e32 v70, v58, v78
	v_exp_f32_e32 v71, v62
	v_sub_f32_e32 v62, v63, v148
	v_add_f32_e32 v70, v59, v70
	v_exp_f32_e32 v72, v62
	v_sub_f32_e32 v62, v64, v148
	v_add_f32_e32 v70, v60, v70
	v_exp_f32_e32 v73, v62
	v_sub_f32_e32 v62, v65, v148
	v_add_f32_e32 v70, v61, v70
	v_exp_f32_e32 v65, v62
	v_add_f32_e32 v62, v71, v70
	v_add_f32_e32 v62, v72, v62
	v_add_f32_e32 v62, v73, v62
	v_add_f32_e32 v70, v65, v62
	v_cvt_pk_bf16_f32 v62, v58, v59
	v_cvt_pk_bf16_f32 v63, v60, v61
	v_cvt_pk_bf16_f32 v64, v71, v72
	v_cvt_pk_bf16_f32 v65, v73, v65
	v_sub_f32_e32 v58, v74, v148
	v_exp_f32_e32 v58, v58
	v_sub_f32_e32 v59, v75, v148
	v_exp_f32_e32 v59, v59
	v_sub_f32_e32 v60, v76, v148
	v_exp_f32_e32 v60, v60
	v_sub_f32_e32 v61, v77, v148
	v_exp_f32_e32 v61, v61
	v_sub_f32_e32 v66, v66, v148
	v_add_f32_e32 v70, v58, v70
	v_exp_f32_e32 v66, v66
	v_sub_f32_e32 v67, v67, v148
	v_add_f32_e32 v70, v59, v70
	v_exp_f32_e32 v67, v67
	v_sub_f32_e32 v68, v68, v148
	v_add_f32_e32 v70, v60, v70
	v_exp_f32_e32 v68, v68
	v_sub_f32_e32 v69, v69, v148
	v_add_f32_e32 v70, v61, v70
	v_exp_f32_e32 v69, v69
	v_add_f32_e32 v70, v66, v70
	v_add_f32_e32 v70, v67, v70
	v_add_f32_e32 v70, v68, v70
	v_add_f32_e32 v70, v69, v70
	v_cvt_pk_bf16_f32 v58, v58, v59
	v_cvt_pk_bf16_f32 v59, v60, v61
	v_cvt_pk_bf16_f32 v60, v66, v67
	v_cvt_pk_bf16_f32 v61, v68, v69
	v_bfe_u32 v104, v104, 3, 6
	v_or_b32_e32 v68, s6, v104
	v_mul_u32_u24_e32 v68, 0x8800, v68
	ds_bpermute_b32 v66, v106, v70
	v_lshlrev_b32_e32 v68, 1, v68
	v_mov_b32_e32 v69, v49
	v_lshl_add_u64 v[68:69], s[44:45], 0, v[68:69]
	v_lshl_add_u64 v[96:97], v[68:69], 0, v[48:49]
	v_lshl_add_u64 v[68:69], s[20:21], 1, v[96:97]
	s_lshl_b32 s2, s8, 1
	s_mov_b32 s3, s73
	v_lshl_add_u64 v[112:113], v[68:69], 0, s[2:3]
	s_waitcnt lgkmcnt(0)
	v_add_f32_e32 v66, v70, v66
	global_load_dwordx4 v[68:71], v[112:113], off
	global_load_dwordx4 v[72:75], v[112:113], off offset:128
	global_load_dwordx4 v[76:79], v[112:113], off offset:256
	global_load_dwordx4 v[80:83], v[112:113], off offset:384
	global_load_dwordx4 v[84:87], v[112:113], off offset:512
	global_load_dwordx4 v[88:91], v[112:113], off offset:640
	global_load_dwordx4 v[92:95], v[112:113], off offset:768
	global_load_dwordx4 v[108:111], v[112:113], off offset:896
	s_nop 0
	global_load_dwordx4 v[112:115], v[112:113], off offset:1024
	v_lshl_add_u64 v[96:97], s[10:11], 1, v[96:97]
	global_load_dwordx4 v[116:119], v[96:97], off
	global_load_dwordx4 v[120:123], v[96:97], off offset:128
	global_load_dwordx4 v[124:127], v[96:97], off offset:256
	global_load_dwordx4 v[128:131], v[96:97], off offset:384
	v_mul_u32_u24_e32 v48, 0xa0, v104
	ds_bpermute_b32 v67, v107, v66
	s_mov_b64 s[6:7], s[72:73]
	v_add_u32_e32 v48, v48, v102
	v_add_u32_e32 v48, 0x70, v48
	s_waitcnt vmcnt(12)
	ds_write_b128 v48, v[68:71]
	s_waitcnt vmcnt(11)
	ds_write_b128 v48, v[72:75] offset:10240
	s_waitcnt vmcnt(10)
	ds_write_b128 v48, v[76:79] offset:20480
	s_waitcnt vmcnt(9)
	ds_write_b128 v48, v[80:83] offset:30720
	s_waitcnt vmcnt(8)
	ds_write_b128 v48, v[84:87] offset:40960
	s_waitcnt vmcnt(7)
	ds_write_b128 v48, v[88:91] offset:51200
	s_waitcnt vmcnt(6)
	ds_write_b128 v48, v[92:95] offset:61440
	s_waitcnt vmcnt(5)
	v_add_u32_e32 v86, 0x11800, v48
	ds_write_b128 v86, v[108:111]
	s_waitcnt vmcnt(4)
	v_add_u32_e32 v86, 0x14000, v48
	ds_write_b128 v86, v[112:115]
	s_waitcnt vmcnt(3)
	v_add_u32_e32 v86, 0x16800, v48
	ds_write_b128 v86, v[116:119]
	s_waitcnt vmcnt(2)
	v_add_u32_e32 v86, 0x19000, v48
	ds_write_b128 v86, v[120:123]
	s_waitcnt vmcnt(1)
	v_add_u32_e32 v86, 0x1b800, v48
	ds_write_b128 v86, v[124:127]
	s_waitcnt vmcnt(0)
	v_add_u32_e32 v86, 0x1e000, v48
	ds_write_b128 v86, v[128:131]
	v_lshl_add_u32 v84, v105, 1, 0
	s_waitcnt lgkmcnt(0)
	s_barrier
	v_add_u32_e32 v48, 0x70, v84
	v_mul_u32_u24_e32 v87, 0xa0, v99
	v_add_u32_e32 v87, v87, v103
	v_add_u32_e32 v87, 0x70, v87
	v_or_b32_e32 v85, s29, v99
	v_mul_u32_u24_e32 v86, 0xa0, v85
	v_add_u32_e32 v86, v86, v48
	ds_read_b128 v[68:71], v86
	ds_read_b128 v[72:75], v86 offset:2560
	ds_read_b128 v[76:79], v86 offset:5120
	ds_read_b128 v[80:83], v86 offset:7680
	v_or_b32_e32 v85, s31, v99
	v_mul_u32_u24_e32 v86, 0xa0, v85
	v_add_u32_e32 v86, v86, v48
	ds_read_b128 v[88:91], v86
	ds_read_b128 v[92:95], v86 offset:2560
	ds_read_b128 v[108:111], v86 offset:5120
	ds_read_b128 v[112:115], v86 offset:7680
	s_waitcnt lgkmcnt(7)
	v_mfma_f32_16x16x32_bf16 v[116:119], v[68:71], v[4:7], 0
	v_or_b32_e32 v85, s35, v99
	v_mul_u32_u24_e32 v86, 0xa0, v85
	v_add_u32_e32 v86, v86, v48
	ds_read_b128 v[68:71], v86
	s_waitcnt lgkmcnt(7)
	v_mfma_f32_16x16x32_bf16 v[120:123], v[72:75], v[4:7], 0
	ds_read_b128 v[72:75], v86 offset:2560
	s_waitcnt lgkmcnt(7)
	v_mfma_f32_16x16x32_bf16 v[124:127], v[76:79], v[4:7], 0
	ds_read_b128 v[76:79], v86 offset:5120
	s_waitcnt lgkmcnt(7)
	v_mfma_f32_16x16x32_bf16 v[128:131], v[80:83], v[4:7], 0
	ds_read_b128 v[80:83], v86 offset:7680
	s_waitcnt lgkmcnt(7)
	v_mfma_f32_16x16x32_bf16 v[116:119], v[88:91], v[0:3], v[116:119]
	v_or_b32_e32 v85, s37, v99
	v_mul_u32_u24_e32 v86, 0xa0, v85
	v_add_u32_e32 v86, v86, v48
	ds_read_b128 v[88:91], v86
	s_waitcnt lgkmcnt(7)
	v_mfma_f32_16x16x32_bf16 v[120:123], v[92:95], v[0:3], v[120:123]
	ds_read_b128 v[92:95], v86 offset:2560
	s_waitcnt lgkmcnt(7)
	v_mfma_f32_16x16x32_bf16 v[124:127], v[108:111], v[0:3], v[124:127]
	ds_read_b128 v[108:111], v86 offset:5120
	s_waitcnt lgkmcnt(7)
	v_mfma_f32_16x16x32_bf16 v[128:131], v[112:115], v[0:3], v[128:131]
	ds_read_b128 v[112:115], v86 offset:7680
	s_waitcnt lgkmcnt(7)
	v_mfma_f32_16x16x32_bf16 v[116:119], v[68:71], v[8:11], v[116:119]
	v_or_b32_e32 v85, s39, v99
	v_mul_u32_u24_e32 v86, 0xa0, v85
	v_add_u32_e32 v86, v86, v48
	ds_read_b128 v[68:71], v86
	s_waitcnt lgkmcnt(7)
	v_mfma_f32_16x16x32_bf16 v[120:123], v[72:75], v[8:11], v[120:123]
	ds_read_b128 v[72:75], v86 offset:2560
	s_waitcnt lgkmcnt(7)
	v_mfma_f32_16x16x32_bf16 v[124:127], v[76:79], v[8:11], v[124:127]
	ds_read_b128 v[76:79], v86 offset:5120
	s_waitcnt lgkmcnt(7)
	v_mfma_f32_16x16x32_bf16 v[128:131], v[80:83], v[8:11], v[128:131]
	ds_read_b128 v[80:83], v86 offset:7680
	s_waitcnt lgkmcnt(7)
	v_mfma_f32_16x16x32_bf16 v[116:119], v[88:91], v[12:15], v[116:119]
	v_or_b32_e32 v85, s51, v99
	v_mul_u32_u24_e32 v86, 0xa0, v85
	v_add_u32_e32 v86, v86, v48
	ds_read_b128 v[88:91], v86
	s_waitcnt lgkmcnt(7)
	v_mfma_f32_16x16x32_bf16 v[120:123], v[92:95], v[12:15], v[120:123]
	ds_read_b128 v[92:95], v86 offset:2560
	s_waitcnt lgkmcnt(7)
	v_mfma_f32_16x16x32_bf16 v[124:127], v[108:111], v[12:15], v[124:127]
	ds_read_b128 v[108:111], v86 offset:5120
	s_waitcnt lgkmcnt(7)
	v_mfma_f32_16x16x32_bf16 v[128:131], v[112:115], v[12:15], v[128:131]
	ds_read_b128 v[112:115], v86 offset:7680
	s_waitcnt lgkmcnt(7)
	v_mfma_f32_16x16x32_bf16 v[116:119], v[68:71], v[16:19], v[116:119]
	v_or_b32_e32 v85, s55, v99
	v_mul_u32_u24_e32 v86, 0xa0, v85
	v_add_u32_e32 v86, v86, v48
	ds_read_b128 v[68:71], v86
	s_waitcnt lgkmcnt(7)
	v_mfma_f32_16x16x32_bf16 v[120:123], v[72:75], v[16:19], v[120:123]
	ds_read_b128 v[72:75], v86 offset:2560
	s_waitcnt lgkmcnt(7)
	v_mfma_f32_16x16x32_bf16 v[124:127], v[76:79], v[16:19], v[124:127]
	ds_read_b128 v[76:79], v86 offset:5120
	s_waitcnt lgkmcnt(7)
	v_mfma_f32_16x16x32_bf16 v[128:131], v[80:83], v[16:19], v[128:131]
	ds_read_b128 v[80:83], v86 offset:7680
	s_waitcnt lgkmcnt(7)
	v_mfma_f32_16x16x32_bf16 v[116:119], v[88:91], v[20:23], v[116:119]
	v_or_b32_e32 v85, s57, v99
	v_mul_u32_u24_e32 v86, 0xa0, v85
	v_add_u32_e32 v86, v86, v48
	ds_read_b128 v[88:91], v86
	s_waitcnt lgkmcnt(7)
	v_mfma_f32_16x16x32_bf16 v[120:123], v[92:95], v[20:23], v[120:123]
	ds_read_b128 v[92:95], v86 offset:2560
	s_waitcnt lgkmcnt(7)
	v_mfma_f32_16x16x32_bf16 v[124:127], v[108:111], v[20:23], v[124:127]
	ds_read_b128 v[108:111], v86 offset:5120
	s_waitcnt lgkmcnt(7)
	v_mfma_f32_16x16x32_bf16 v[128:131], v[112:115], v[20:23], v[128:131]
	ds_read_b128 v[112:115], v86 offset:7680
	s_waitcnt lgkmcnt(7)
	v_mfma_f32_16x16x32_bf16 v[116:119], v[68:71], v[24:27], v[116:119]
	v_add_u32_e32 v86, 0x16800, v87
	ds_read_b128 v[68:71], v86
	s_waitcnt lgkmcnt(7)
	v_mfma_f32_16x16x32_bf16 v[120:123], v[72:75], v[24:27], v[120:123]
	ds_read_b128 v[72:75], v86 offset:2560
	s_waitcnt lgkmcnt(7)
	v_mfma_f32_16x16x32_bf16 v[124:127], v[76:79], v[24:27], v[124:127]
	ds_read_b128 v[76:79], v86 offset:5120
	s_waitcnt lgkmcnt(7)
	v_mfma_f32_16x16x32_bf16 v[128:131], v[80:83], v[24:27], v[128:131]
	ds_read_b128 v[80:83], v86 offset:7680
	s_waitcnt lgkmcnt(7)
	v_mfma_f32_16x16x32_bf16 v[116:119], v[88:91], v[28:31], v[116:119]
	ds_read_b128 v[88:91], v86 offset:64
	s_waitcnt lgkmcnt(7)
	v_mfma_f32_16x16x32_bf16 v[120:123], v[92:95], v[28:31], v[120:123]
	ds_read_b128 v[92:95], v86 offset:2624
	s_waitcnt lgkmcnt(7)
	v_mfma_f32_16x16x32_bf16 v[124:127], v[108:111], v[28:31], v[124:127]
	ds_read_b128 v[108:111], v86 offset:5184
	s_waitcnt lgkmcnt(7)
	v_mfma_f32_16x16x32_bf16 v[128:131], v[112:115], v[28:31], v[128:131]
	ds_read_b128 v[112:115], v86 offset:7744
	s_waitcnt lgkmcnt(7)
	v_mfma_f32_16x16x32_bf16 v[116:119], v[68:71], v[32:35], v[116:119]
	v_add_u32_e32 v86, 0x19000, v87
	ds_read_b128 v[68:71], v86
	s_waitcnt lgkmcnt(7)
	v_mfma_f32_16x16x32_bf16 v[120:123], v[72:75], v[32:35], v[120:123]
	ds_read_b128 v[72:75], v86 offset:2560
	s_waitcnt lgkmcnt(7)
	v_mfma_f32_16x16x32_bf16 v[124:127], v[76:79], v[32:35], v[124:127]
	ds_read_b128 v[76:79], v86 offset:5120
	s_waitcnt lgkmcnt(7)
	v_mfma_f32_16x16x32_bf16 v[128:131], v[80:83], v[32:35], v[128:131]
	ds_read_b128 v[80:83], v86 offset:7680
	s_waitcnt lgkmcnt(7)
	v_mfma_f32_16x16x32_bf16 v[116:119], v[88:91], v[36:39], v[116:119]
	ds_read_b128 v[88:91], v86 offset:64
	s_waitcnt lgkmcnt(7)
	v_mfma_f32_16x16x32_bf16 v[120:123], v[92:95], v[36:39], v[120:123]
	ds_read_b128 v[92:95], v86 offset:2624
	s_waitcnt lgkmcnt(7)
	v_mfma_f32_16x16x32_bf16 v[124:127], v[108:111], v[36:39], v[124:127]
	ds_read_b128 v[108:111], v86 offset:5184
	s_waitcnt lgkmcnt(7)
	v_mfma_f32_16x16x32_bf16 v[128:131], v[112:115], v[36:39], v[128:131]
	ds_read_b128 v[112:115], v86 offset:7744
	s_waitcnt lgkmcnt(7)
	v_mfma_f32_16x16x32_bf16 v[116:119], v[68:71], v[40:43], v[116:119]
	v_add_u32_e32 v86, 0x1b800, v87
	ds_read_b128 v[68:71], v86
	s_waitcnt lgkmcnt(7)
	v_mfma_f32_16x16x32_bf16 v[120:123], v[72:75], v[40:43], v[120:123]
	ds_read_b128 v[72:75], v86 offset:2560
	s_waitcnt lgkmcnt(7)
	v_mfma_f32_16x16x32_bf16 v[124:127], v[76:79], v[40:43], v[124:127]
	ds_read_b128 v[76:79], v86 offset:5120
	s_waitcnt lgkmcnt(7)
	v_mfma_f32_16x16x32_bf16 v[128:131], v[80:83], v[40:43], v[128:131]
	ds_read_b128 v[80:83], v86 offset:7680
	s_waitcnt lgkmcnt(7)
	v_mfma_f32_16x16x32_bf16 v[116:119], v[88:91], v[44:47], v[116:119]
	ds_read_b128 v[88:91], v86 offset:64
	s_waitcnt lgkmcnt(7)
	v_mfma_f32_16x16x32_bf16 v[120:123], v[92:95], v[44:47], v[120:123]
	ds_read_b128 v[92:95], v86 offset:2624
	s_waitcnt lgkmcnt(7)
	v_mfma_f32_16x16x32_bf16 v[124:127], v[108:111], v[44:47], v[124:127]
	ds_read_b128 v[108:111], v86 offset:5184
	s_waitcnt lgkmcnt(7)
	v_mfma_f32_16x16x32_bf16 v[128:131], v[112:115], v[44:47], v[128:131]
	ds_read_b128 v[112:115], v86 offset:7744
	s_waitcnt lgkmcnt(7)
	v_mfma_f32_16x16x32_bf16 v[116:119], v[68:71], v[50:53], v[116:119]
	v_add_u32_e32 v86, 0x1e000, v87
	ds_read_b128 v[68:71], v86
	s_waitcnt lgkmcnt(7)
	v_mfma_f32_16x16x32_bf16 v[120:123], v[72:75], v[50:53], v[120:123]
	ds_read_b128 v[72:75], v86 offset:2560
	s_waitcnt lgkmcnt(7)
	v_mfma_f32_16x16x32_bf16 v[124:127], v[76:79], v[50:53], v[124:127]
	ds_read_b128 v[76:79], v86 offset:5120
	s_waitcnt lgkmcnt(7)
	v_mfma_f32_16x16x32_bf16 v[128:131], v[80:83], v[50:53], v[128:131]
	ds_read_b128 v[80:83], v86 offset:7680
	s_waitcnt lgkmcnt(7)
	v_mfma_f32_16x16x32_bf16 v[116:119], v[88:91], v[54:57], v[116:119]
	ds_read_b128 v[88:91], v86 offset:64
	s_waitcnt lgkmcnt(7)
	v_mfma_f32_16x16x32_bf16 v[120:123], v[92:95], v[54:57], v[120:123]
	ds_read_b128 v[92:95], v86 offset:2624
	s_waitcnt lgkmcnt(7)
	v_mfma_f32_16x16x32_bf16 v[124:127], v[108:111], v[54:57], v[124:127]
	ds_read_b128 v[108:111], v86 offset:5184
	s_waitcnt lgkmcnt(7)
	v_mfma_f32_16x16x32_bf16 v[128:131], v[112:115], v[54:57], v[128:131]
	ds_read_b128 v[112:115], v86 offset:7744
	s_waitcnt lgkmcnt(7)
	v_mfma_f32_16x16x32_bf16 v[116:119], v[68:71], v[62:65], v[116:119]
	s_waitcnt lgkmcnt(6)
	v_mfma_f32_16x16x32_bf16 v[120:123], v[72:75], v[62:65], v[120:123]
	s_waitcnt lgkmcnt(5)
	v_mfma_f32_16x16x32_bf16 v[124:127], v[76:79], v[62:65], v[124:127]
	s_waitcnt lgkmcnt(4)
	v_mfma_f32_16x16x32_bf16 v[128:131], v[80:83], v[62:65], v[128:131]
	s_waitcnt lgkmcnt(3)
	v_mfma_f32_16x16x32_bf16 v[4:7], v[88:91], v[58:61], v[116:119]
	s_waitcnt lgkmcnt(2)
	v_mfma_f32_16x16x32_bf16 v[8:11], v[92:95], v[58:61], v[120:123]
	s_waitcnt lgkmcnt(1)
	v_mfma_f32_16x16x32_bf16 v[12:15], v[108:111], v[58:61], v[124:127]
	s_waitcnt lgkmcnt(0)
	v_mfma_f32_16x16x32_bf16 v[0:3], v[112:115], v[58:61], v[128:131]
	v_add_f32_e32 v16, v66, v67
	v_rcp_f32_e32 v18, v16
	v_lshl_add_u64 v[16:17], v[100:101], 1, s[42:43]
	v_lshl_add_u64 v[16:17], v[16:17], 0, s[6:7]
	v_mov_b32_e32 v99, v49
	v_mul_f32_e32 v4, v18, v4
	v_mul_f32_e32 v5, v18, v5
	v_cvt_pk_bf16_f32 v4, v4, v5
	v_mul_f32_e32 v5, v18, v6
	v_lshl_add_u64 v[16:17], v[16:17], 0, v[98:99]
	v_mul_f32_e32 v6, v18, v7
	v_cvt_pk_bf16_f32 v5, v5, v6
	global_store_dwordx2 v[16:17], v[4:5], off
	v_mul_f32_e32 v4, v18, v8
	v_mul_f32_e32 v5, v18, v9
	v_cvt_pk_bf16_f32 v4, v4, v5
	v_mul_f32_e32 v5, v18, v10
	v_mul_f32_e32 v6, v18, v11
	v_cvt_pk_bf16_f32 v5, v5, v6
	global_store_dwordx2 v[16:17], v[4:5], off offset:32
	v_mul_f32_e32 v4, v18, v12
	v_mul_f32_e32 v5, v18, v13
	v_mul_f32_e32 v0, v18, v0
	v_mul_f32_e32 v1, v18, v1
	s_addk_i32 s64, 0x100
	v_cvt_pk_bf16_f32 v4, v4, v5
	v_mul_f32_e32 v5, v18, v14
	v_cvt_pk_bf16_f32 v0, v0, v1
	v_mul_f32_e32 v1, v18, v2
	s_cmpk_eq_i32 s64, 0x1000
	v_mul_f32_e32 v6, v18, v15
	v_cvt_pk_bf16_f32 v5, v5, v6
	global_store_dwordx2 v[16:17], v[4:5], off offset:64
	v_mul_f32_e32 v2, v18, v3
	v_cvt_pk_bf16_f32 v1, v1, v2
	global_store_dwordx2 v[16:17], v[0:1], off offset:96
	s_barrier
	s_cbranch_scc1 .LBB0_221
.LBB0_167:
	s_or_b32 s40, s64, s63
	s_ashr_i32 s2, s40, 9
	s_lshl_b32 s3, s2, 8
	v_mov_b32 v104, v220
	s_add_i32 s10, s3, 0x8000
	v_ashrrev_i32_e32 v62, 3, v104
	s_ashr_i32 s11, s10, 31
	v_cmp_lt_i32_e32 vcc, s68, v62
	s_and_saveexec_b64 s[6:7], vcc
	s_xor_b64 s[6:7], exec, s[6:7]
	v_add_u32_e32 v48, 0xfffffdc0, v62
	v_lshl_add_u64 v[2:3], s[10:11], 0, v[48:49]
	s_or_saveexec_b64 s[6:7], s[6:7]
	s_ashr_i32 s3, s2, 31
	s_lshl_b64 s[20:21], s[2:3], 12
	s_or_b64 s[2:3], s[20:21], s[8:9]
	s_xor_b64 exec, exec, s[6:7]
	v_ashrrev_i32_e32 v63, 31, v62
	v_lshl_add_u64 v[2:3], s[2:3], 0, v[62:63]
	s_or_b64 exec, exec, s[6:7]
	s_bfe_u32 s40, s40, 0x40005
	s_lshl_b32 s6, s40, 7
	v_lshlrev_b32_e32 v0, 3, v104
	s_add_u32 s6, s12, s6
	v_and_b32_e32 v0, 56, v0
	s_addc_u32 s7, s13, 0
	v_lshlrev_b32_e32 v48, 1, v0
	v_lshl_add_u64 v[0:1], s[6:7], 0, v[48:49]
	v_lshlrev_b64 v[2:3], 11, v[2:3]
	v_lshl_add_u64 v[2:3], v[0:1], 0, v[2:3]
	global_load_dwordx4 v[8:11], v[2:3], off
	v_add_u32_e32 v2, 0x200, v104
	v_ashrrev_i32_e32 v64, 3, v2
	v_cmp_lt_i32_e32 vcc, s68, v64
	s_and_saveexec_b64 s[6:7], vcc
	s_xor_b64 s[6:7], exec, s[6:7]
	v_add_u32_e32 v2, 0xfffffdc0, v64
	v_mov_b32_e32 v3, v49
	v_lshl_add_u64 v[2:3], s[10:11], 0, v[2:3]
	s_andn2_saveexec_b64 s[6:7], s[6:7]
	v_ashrrev_i32_e32 v65, 31, v64
	v_lshl_add_u64 v[2:3], s[2:3], 0, v[64:65]
	s_or_b64 exec, exec, s[6:7]
	v_lshlrev_b64 v[2:3], 11, v[2:3]
	v_lshl_add_u64 v[2:3], v[0:1], 0, v[2:3]
	global_load_dwordx4 v[12:15], v[2:3], off
	v_add_u32_e32 v2, 0x400, v104
	s_waitcnt vmcnt(0)
	v_ashrrev_i32_e32 v66, 3, v2
	v_cmp_lt_i32_e32 vcc, s68, v66
	s_and_saveexec_b64 s[6:7], vcc
	s_xor_b64 s[6:7], exec, s[6:7]
	v_add_u32_e32 v2, 0xfffffdc0, v66
	v_mov_b32_e32 v3, v49
	v_lshl_add_u64 v[2:3], s[10:11], 0, v[2:3]
	s_andn2_saveexec_b64 s[6:7], s[6:7]
	v_ashrrev_i32_e32 v67, 31, v66
	v_lshl_add_u64 v[2:3], s[2:3], 0, v[66:67]
	s_or_b64 exec, exec, s[6:7]
	v_lshlrev_b64 v[2:3], 11, v[2:3]
	v_lshl_add_u64 v[2:3], v[0:1], 0, v[2:3]
	global_load_dwordx4 v[16:19], v[2:3], off
	v_add_u32_e32 v2, 0x600, v104
	v_ashrrev_i32_e32 v68, 3, v2
	v_cmp_lt_i32_e32 vcc, s68, v68
	s_and_saveexec_b64 s[6:7], vcc
	s_xor_b64 s[6:7], exec, s[6:7]
	v_add_u32_e32 v2, 0xfffffdc0, v68
	v_mov_b32_e32 v3, v49
	v_lshl_add_u64 v[2:3], s[10:11], 0, v[2:3]
	s_andn2_saveexec_b64 s[6:7], s[6:7]
	v_ashrrev_i32_e32 v69, 31, v68
	v_lshl_add_u64 v[2:3], s[2:3], 0, v[68:69]
	s_or_b64 exec, exec, s[6:7]
	v_lshlrev_b64 v[2:3], 11, v[2:3]
	v_lshl_add_u64 v[2:3], v[0:1], 0, v[2:3]
	global_load_dwordx4 v[20:23], v[2:3], off
	v_add_u32_e32 v2, 0x800, v104
	s_waitcnt vmcnt(10)
	v_ashrrev_i32_e32 v70, 3, v2
	v_cmp_lt_i32_e32 vcc, s68, v70
	s_and_saveexec_b64 s[6:7], vcc
	s_xor_b64 s[6:7], exec, s[6:7]
	v_add_u32_e32 v2, 0xfffffdc0, v70
	v_mov_b32_e32 v3, v49
	v_lshl_add_u64 v[2:3], s[10:11], 0, v[2:3]
	s_andn2_saveexec_b64 s[6:7], s[6:7]
	v_ashrrev_i32_e32 v71, 31, v70
	v_lshl_add_u64 v[2:3], s[2:3], 0, v[70:71]
	s_or_b64 exec, exec, s[6:7]
	v_lshlrev_b64 v[2:3], 11, v[2:3]
	v_lshl_add_u64 v[2:3], v[0:1], 0, v[2:3]
	global_load_dwordx4 v[24:27], v[2:3], off
	v_add_u32_e32 v2, 0xa00, v104
	v_ashrrev_i32_e32 v72, 3, v2
	v_cmp_lt_i32_e32 vcc, s68, v72
	s_and_saveexec_b64 s[6:7], vcc
	s_xor_b64 s[6:7], exec, s[6:7]
	v_add_u32_e32 v2, 0xfffffdc0, v72
	v_mov_b32_e32 v3, v49
	v_lshl_add_u64 v[2:3], s[10:11], 0, v[2:3]
	s_andn2_saveexec_b64 s[6:7], s[6:7]
	v_ashrrev_i32_e32 v73, 31, v72
	v_lshl_add_u64 v[2:3], s[2:3], 0, v[72:73]
	s_or_b64 exec, exec, s[6:7]
	v_lshlrev_b64 v[2:3], 11, v[2:3]
	v_lshl_add_u64 v[2:3], v[0:1], 0, v[2:3]
	global_load_dwordx4 v[28:31], v[2:3], off
	v_add_u32_e32 v2, 0xc00, v104
	s_waitcnt vmcnt(11)
	v_ashrrev_i32_e32 v74, 3, v2
	v_cmp_lt_i32_e32 vcc, s68, v74
	s_and_saveexec_b64 s[6:7], vcc
	s_xor_b64 s[6:7], exec, s[6:7]
	v_add_u32_e32 v2, 0xfffffdc0, v74
	v_mov_b32_e32 v3, v49
	v_lshl_add_u64 v[2:3], s[10:11], 0, v[2:3]
	s_andn2_saveexec_b64 s[6:7], s[6:7]
	v_ashrrev_i32_e32 v75, 31, v74
	v_lshl_add_u64 v[2:3], s[2:3], 0, v[74:75]
	s_or_b64 exec, exec, s[6:7]
	v_lshlrev_b64 v[2:3], 11, v[2:3]
	v_lshl_add_u64 v[2:3], v[0:1], 0, v[2:3]
	global_load_dwordx4 v[32:35], v[2:3], off
	v_add_u32_e32 v2, 0xe00, v104
	v_ashrrev_i32_e32 v76, 3, v2
	v_cmp_lt_i32_e32 vcc, s68, v76
	s_and_saveexec_b64 s[6:7], vcc
	s_xor_b64 s[6:7], exec, s[6:7]
	v_add_u32_e32 v2, 0xfffffdc0, v76
	v_mov_b32_e32 v3, v49
	v_lshl_add_u64 v[2:3], s[10:11], 0, v[2:3]
	s_andn2_saveexec_b64 s[6:7], s[6:7]
	v_ashrrev_i32_e32 v77, 31, v76
	v_lshl_add_u64 v[2:3], s[2:3], 0, v[76:77]
	s_or_b64 exec, exec, s[6:7]
	v_lshlrev_b64 v[2:3], 11, v[2:3]
	v_lshl_add_u64 v[2:3], v[0:1], 0, v[2:3]
	global_load_dwordx4 v[36:39], v[2:3], off
	v_add_u32_e32 v2, 0x1000, v104
	s_waitcnt vmcnt(12)
	v_ashrrev_i32_e32 v78, 3, v2
	v_cmp_lt_i32_e32 vcc, s68, v78
	s_and_saveexec_b64 s[6:7], vcc
	s_xor_b64 s[6:7], exec, s[6:7]
	v_add_u32_e32 v2, 0xfffffdc0, v78
	v_mov_b32_e32 v3, v49
	v_lshl_add_u64 v[2:3], s[10:11], 0, v[2:3]
	s_andn2_saveexec_b64 s[6:7], s[6:7]
	v_ashrrev_i32_e32 v79, 31, v78
	v_lshl_add_u64 v[2:3], s[2:3], 0, v[78:79]
	s_or_b64 exec, exec, s[6:7]
	v_lshlrev_b64 v[2:3], 11, v[2:3]
	v_lshl_add_u64 v[2:3], v[0:1], 0, v[2:3]
	global_load_dwordx4 v[40:43], v[2:3], off
	v_add_u32_e32 v2, 0x1200, v104
	v_ashrrev_i32_e32 v80, 3, v2
	v_cmp_lt_i32_e32 vcc, s68, v80
	s_and_saveexec_b64 s[6:7], vcc
	s_xor_b64 s[6:7], exec, s[6:7]
	v_add_u32_e32 v2, 0xfffffdc0, v80
	v_mov_b32_e32 v3, v49
	v_lshl_add_u64 v[2:3], s[10:11], 0, v[2:3]
	s_andn2_saveexec_b64 s[6:7], s[6:7]
	v_ashrrev_i32_e32 v81, 31, v80
	v_lshl_add_u64 v[2:3], s[2:3], 0, v[80:81]
	s_or_b64 exec, exec, s[6:7]
	v_lshlrev_b64 v[2:3], 11, v[2:3]
	v_lshl_add_u64 v[2:3], v[0:1], 0, v[2:3]
	global_load_dwordx4 v[44:47], v[2:3], off
	v_add_u32_e32 v2, 0x1400, v104
	s_waitcnt vmcnt(13)
	v_ashrrev_i32_e32 v82, 3, v2
	v_cmp_lt_i32_e32 vcc, s68, v82
	s_and_saveexec_b64 s[6:7], vcc
	s_xor_b64 s[6:7], exec, s[6:7]
	v_add_u32_e32 v2, 0xfffffdc0, v82
	v_mov_b32_e32 v3, v49
	v_lshl_add_u64 v[2:3], s[10:11], 0, v[2:3]
	s_andn2_saveexec_b64 s[6:7], s[6:7]
	v_ashrrev_i32_e32 v83, 31, v82
	v_lshl_add_u64 v[2:3], s[2:3], 0, v[82:83]
	s_or_b64 exec, exec, s[6:7]
	v_lshlrev_b64 v[2:3], 11, v[2:3]
	v_lshl_add_u64 v[2:3], v[0:1], 0, v[2:3]
	global_load_dwordx4 v[50:53], v[2:3], off
	v_add_u32_e32 v2, 0x1600, v104
	v_ashrrev_i32_e32 v84, 3, v2
	v_cmp_lt_i32_e32 vcc, s68, v84
	s_and_saveexec_b64 s[6:7], vcc
	s_xor_b64 s[6:7], exec, s[6:7]
	v_add_u32_e32 v2, 0xfffffdc0, v84
	v_mov_b32_e32 v3, v49
	v_lshl_add_u64 v[2:3], s[10:11], 0, v[2:3]
	s_andn2_saveexec_b64 s[6:7], s[6:7]
	v_ashrrev_i32_e32 v85, 31, v84
	v_lshl_add_u64 v[2:3], s[2:3], 0, v[84:85]
	s_or_b64 exec, exec, s[6:7]
	v_lshlrev_b64 v[2:3], 11, v[2:3]
	v_lshl_add_u64 v[2:3], v[0:1], 0, v[2:3]
	global_load_dwordx4 v[54:57], v[2:3], off
	v_add_u32_e32 v2, 0x1800, v104
	s_waitcnt vmcnt(14)
	v_ashrrev_i32_e32 v86, 3, v2
	v_cmp_lt_i32_e32 vcc, s68, v86
	s_and_saveexec_b64 s[6:7], vcc
	s_xor_b64 s[6:7], exec, s[6:7]
	v_add_u32_e32 v2, 0xfffffdc0, v86
	v_mov_b32_e32 v3, v49
	v_lshl_add_u64 v[2:3], s[10:11], 0, v[2:3]
	s_andn2_saveexec_b64 s[6:7], s[6:7]
	v_ashrrev_i32_e32 v87, 31, v86
	v_lshl_add_u64 v[2:3], s[2:3], 0, v[86:87]
	s_or_b64 exec, exec, s[6:7]
	s_lshl_b32 s6, s40, 6
	s_add_u32 s2, s24, s20
	v_and_b32_e32 v99, 15, v104
	s_addc_u32 s3, s23, s21
	v_lshlrev_b64 v[2:3], 11, v[2:3]
	v_or_b32_e32 v88, s2, v99
	v_mov_b32_e32 v89, s3
	v_lshl_add_u64 v[0:1], v[0:1], 0, v[2:3]
	v_lshlrev_b64 v[2:3], 11, v[88:89]
	v_bfe_u32 v63, v104, 4, 2
	v_lshl_add_u64 v[2:3], s[46:47], 0, v[2:3]
	s_mov_b32 s3, s73
	s_lshl_b32 s2, s6, 1
	v_lshl_add_u64 v[2:3], v[2:3], 0, s[2:3]
	v_lshlrev_b32_e32 v4, 4, v63
	v_mov_b32_e32 v5, v49
	v_lshl_add_u64 v[2:3], v[2:3], 0, v[4:5]
	global_load_dwordx4 v[58:61], v[0:1], off
	global_load_dwordx4 v[4:7], v[2:3], off
	s_nop 0
	global_load_dwordx4 v[0:3], v[2:3], off offset:64
	s_mov_b64 s[72:73], s[2:3]
	s_movk_i32 s2, 0x1d1
	v_cmp_gt_i32_e32 vcc, s2, v104
	s_and_saveexec_b64 s[2:3], vcc
	s_cbranch_execz .LBB0_166
	s_mulk_i32 s40, 0x1d1
	s_waitcnt vmcnt(16)
	v_add_u32_e32 v90, s40, v104
	v_ashrrev_i32_e32 v91, 31, v90
	v_lshl_add_u64 v[90:91], v[90:91], 2, s[48:49]
	global_load_dword v65, v[90:91], off
	v_lshl_add_u32 v67, v104, 2, 0
	v_add_u32_e32 v67, 0x20900, v67
	s_waitcnt vmcnt(0)
	v_mul_f32_e32 v65, 0x3fb8aa3b, v65
	ds_write_b32 v67, v65
	s_branch .LBB0_166
